# M5 + sliver MFMA variant selection by one scalar branch (flag VALU/SALU removed from compute-block tail), dtype comment line added
# speedup vs baseline: 1.0078x; 1.0044x over previous
; #define PG8_SB(B) __builtin_amdgcn_rcpf(1.f + expneg(B))
; #define PG8_SB(B) __builtin_amdgcn_rcpf(1.f + expneg(B))
; #define PG8_STAGE(bufoff, gbase, voff) do { _Pragma("unroll") for (int _i = 0; _i < 2; ++_i) \
;         __builtin_amdgcn_global_load_lds((const unsigned*)((const char*)(gbase) + (size_t)_i * qstep + (voff)[0]), (PG8_LAS unsigned*)(lds + (bufoff) + ldsw + _i * 8192), 16, 0, 0); } while (0)
; #define PG8_LDA(dst, b, h) do { _Pragma("unroll") for (int m = 0; m < 4; ++m) _Pragma("unroll") for (int k = 0; k < 2; ++k) dst[m][k] = *(const PG8_LAS bf16x8*)(lds + PG8_SA(b, h) + aoff + m * 2048 + k * 1024); } while (0)
; #define PG8_LDB(dst, b, h) do { _Pragma("unroll") for (int n = 0; n < 2; ++n) _Pragma("unroll") for (int k = 0; k < 2; ++k) dst[n][k] = *(const PG8_LAS bf16x8*)(lds + PG8_SB(b, h) + boff + n * 2048 + k * 1024); } while (0)
; #define PG8_WAIT_V89() do { if constexpr (SLIVER) PG8_WAIT_V(9); else PG8_WAIT_V(8); } while (0)
; #define PG8_STAGE_S(b, gbase) do { if constexpr (SLIVER) __builtin_amdgcn_global_load_lds((const unsigned*)((const char*)(gbase) + voffS), (PG8_LAS unsigned*)(lds + STAGE_BYTES + (b) * 2048 + wid * 256), 4, 0, 0); } while (0)
; template <class Epi, class Sched, bool ALIGN_EPI = false, bool SP2 = false, bool SLIVER = false>
; __device__ __forceinline__ void gemm_phase(PG8_LAS unsigned char* lds, const Gemm g, const Sched& S, const Epi& E) {
;     ...
;         for (int t = 0; t < nt; t += 2) {
;             const bool last = (t == nt - 2);
;             const char* a1 = cA + (size_t)(t + 1) * kstep;
;             const char* a2 = last ? nA : cA + (size_t)(t + 2) * kstep; const char* b2 = last ? nB : cB + (size_t)(t + 2) * kstep;
;             const char* a3 = a2 + kstep; const char* b3 = b2 + kstep;
;             const char* s1 = cS + (size_t)(t + 1) * kstep; const char* s2 = last ? nS : cS + (size_t)(t + 2) * kstep;
;             if (last && has_next) S.a_ready(nxt);
;             if constexpr (SP2) {
;             PG8_LDB(B0, 0, 0); PG8_LDB(B1, 0, 1); PG8_SCHED; PG8_LDA(At, 0, 0); PG8_STAGE(PG8_SA(1, 1), a1 + hstep, voffA); PG8_STAGE_S(1, s1);
;             PG8_WAIT_V89(); PG8_WAIT_L(0); PG8_BAR; PG8_MMA(0, 0, At, B0); PG8_MMA(0, 1, At, B1); PG8_BAR; PG8_SCHED;
;             PG8_LDA(At, 0, 1); PG8_LDS_S(0); PG8_STAGE(PG8_SB(0, 0), b2, voffB); PG8_STAGE(PG8_SB(0, 1), b2 + hstep, voffB); PG8_STAGE(PG8_SA(0, 0), a2, voffA);
.LBB0_497:
	s_barrier
	s_setprio 0
	s_mov_b64 s[86:87], 0x4000400
	s_mov_b64 s[88:89], 0x4000800
	s_mov_b64 s[68:69], 0x4000c00
	s_add_i32 s67, s67, 2
	s_add_u32 s80, s80, 0x100
	s_addc_u32 s81, s81, 0
	s_cmp_ge_u32 s67, s3
	s_cbranch_scc1 .LBB0_508
.LBB0_498:
	s_cmp_eq_u32 s66, s80
	s_cselect_b64 s[86:87], -1, 0
	s_add_u32 s40, s16, s80
	s_addc_u32 s41, s17, s81
	s_add_u32 s68, s40, 0x100
	s_addc_u32 s69, s41, 0
	s_and_b64 s[40:41], s[86:87], exec
	s_cselect_b32 s41, s55, s69
	s_cselect_b32 s40, s54, s68
	s_add_u32 s76, s12, s80
	s_addc_u32 s77, s13, s81
	s_add_i32 s78, 0, 0x10000
	s_and_b64 s[68:69], s[86:87], exec
	v_add_u32_e32 v138, s78, v239
	s_cselect_b32 s69, s83, s77
	s_cselect_b32 s68, s82, s76
	s_add_i32 s76, 0, 0x14000
	ds_read_b128 v[146:149], v138
	ds_read_b128 v[150:153], v138 offset:1024
	ds_read_b128 v[154:157], v138 offset:2048
	ds_read_b128 v[158:161], v138 offset:3072
	v_add_u32_e32 v138, s76, v239
	ds_read_b128 v[166:169], v138
	ds_read_b128 v[170:173], v138 offset:1024
	ds_read_b128 v[174:177], v138 offset:2048
	ds_read_b128 v[162:165], v138 offset:3072
	v_lshl_add_u64 v[208:209], v[188:189], 0, s[80:81]
	v_lshl_add_u64 v[224:225], v[208:209], 0, s[34:35]
	s_add_i32 m0, s96, 0xc000
	s_mov_b64 s[88:89], 0x120080
	ds_read_b128 v[138:141], v242
	ds_read_b128 v[142:145], v242 offset:1024
	ds_read_b128 v[180:183], v242 offset:2048
	ds_read_b128 v[184:187], v242 offset:3072
	ds_read_b128 v[192:195], v242 offset:4096
	ds_read_b128 v[196:199], v242 offset:5120
	ds_read_b128 v[200:203], v242 offset:6144
	ds_read_b128 v[220:223], v242 offset:7168
	global_load_lds_dwordx4 v[224:225], off
	v_lshl_add_u64 v[208:209], v[208:209], 0, s[88:89]
	s_add_i32 m0, s96, 0xe000
	s_nop 0
	global_load_lds_dwordx4 v[208:209], off
	v_lshl_add_u64 v[208:209], v[190:191], 0, s[80:81]
	s_add_i32 m0, s94, 0x20800
	s_nop 0
	global_load_lds_dword v[208:209], off
	s_waitcnt vmcnt(9)
	s_waitcnt lgkmcnt(0)
	s_setprio 1
	s_barrier
	v_mfma_f32_16x16x32_bf16 v[134:137], v[146:149], v[138:141], v[134:137]
	v_mfma_f32_16x16x32_bf16 v[130:133], v[154:157], v[138:141], v[130:133]
	v_mfma_f32_16x16x32_bf16 v[126:129], v[146:149], v[180:183], v[126:129]
	v_mfma_f32_16x16x32_bf16 v[122:125], v[154:157], v[180:183], v[122:125]
	v_mfma_f32_16x16x32_bf16 v[118:121], v[146:149], v[192:195], v[118:121]
	v_mfma_f32_16x16x32_bf16 v[114:117], v[154:157], v[192:195], v[114:117]
	v_mfma_f32_16x16x32_bf16 v[110:113], v[146:149], v[200:203], v[110:113]
	v_mfma_f32_16x16x32_bf16 v[106:109], v[154:157], v[200:203], v[106:109]
	v_mfma_f32_16x16x32_bf16 v[134:137], v[150:153], v[142:145], v[134:137]
	v_mfma_f32_16x16x32_bf16 v[130:133], v[158:161], v[142:145], v[130:133]
	v_mfma_f32_16x16x32_bf16 v[126:129], v[150:153], v[184:187], v[126:129]
	v_mfma_f32_16x16x32_bf16 v[122:125], v[158:161], v[184:187], v[122:125]
	v_mfma_f32_16x16x32_bf16 v[118:121], v[150:153], v[196:199], v[118:121]
	v_mfma_f32_16x16x32_bf16 v[114:117], v[158:161], v[196:199], v[114:117]
	v_mfma_f32_16x16x32_bf16 v[110:113], v[150:153], v[220:223], v[110:113]
	v_mfma_f32_16x16x32_bf16 v[106:109], v[158:161], v[220:223], v[106:109]
	s_setprio 0
	s_setprio 1
	v_mfma_f32_16x16x32_bf16 v[102:105], v[166:169], v[138:141], v[102:105]
	v_mfma_f32_16x16x32_bf16 v[98:101], v[174:177], v[138:141], v[98:101]
	v_mfma_f32_16x16x32_bf16 v[90:93], v[166:169], v[180:183], v[90:93]
	v_mfma_f32_16x16x32_bf16 v[86:89], v[174:177], v[180:183], v[86:89]
	v_mfma_f32_16x16x32_bf16 v[78:81], v[166:169], v[192:195], v[78:81]
	v_mfma_f32_16x16x32_bf16 v[74:77], v[174:177], v[192:195], v[74:77]
	v_mfma_f32_16x16x32_bf16 v[70:73], v[166:169], v[200:203], v[70:73]
	v_mfma_f32_16x16x32_bf16 v[66:69], v[174:177], v[200:203], v[66:69]
	v_mfma_f32_16x16x32_bf16 v[102:105], v[170:173], v[142:145], v[102:105]
	v_mfma_f32_16x16x32_bf16 v[98:101], v[162:165], v[142:145], v[98:101]
	v_mfma_f32_16x16x32_bf16 v[90:93], v[170:173], v[184:187], v[90:93]
	v_mfma_f32_16x16x32_bf16 v[86:89], v[162:165], v[184:187], v[86:89]
	v_mfma_f32_16x16x32_bf16 v[78:81], v[170:173], v[196:199], v[78:81]
	v_mfma_f32_16x16x32_bf16 v[74:77], v[162:165], v[196:199], v[74:77]
	v_mfma_f32_16x16x32_bf16 v[70:73], v[170:173], v[220:223], v[70:73]
	v_mfma_f32_16x16x32_bf16 v[66:69], v[162:165], v[220:223], v[66:69]
	s_barrier
	s_setprio 0
	s_add_i32 s77, 0, 0x20000
	v_lshl_add_u64 v[192:193], s[68:69], 0, v[212:213]
	s_add_i32 s68, s78, s95
	v_add_u32_e32 v178, s77, v240
	v_add_u32_e32 v184, s77, v241
	s_mov_b32 m0, s68
	s_mov_b64 s[88:89], 0x60000
	ds_read_b128 v[138:141], v242 offset:16384
	ds_read_b128 v[142:145], v242 offset:17408
	ds_read_b128 v[196:199], v242 offset:18432
	ds_read_b128 v[200:203], v242 offset:19456
	ds_read_b128 v[220:223], v242 offset:20480
	ds_read_b128 v[224:227], v242 offset:21504
	ds_read_b128 v[228:231], v242 offset:22528
	ds_read_b128 v[232:235], v242 offset:23552
	ds_read_b128 v[180:183], v178
	ds_read_b128 v[184:187], v184
	global_load_lds_dwordx4 v[192:193], off
	v_lshl_add_u64 v[194:195], v[192:193], 0, s[88:89]
	s_add_i32 m0, s68, 0x2000
	s_add_i32 s68, s76, s95
	global_load_lds_dwordx4 v[194:195], off
	v_lshl_add_u64 v[194:195], v[192:193], 0, s[24:25]
	s_mov_b32 m0, s68
	s_nop 0
	global_load_lds_dwordx4 v[194:195], off
	v_lshl_add_u64 v[194:195], v[192:193], 0, s[14:15]
	s_add_i32 m0, s68, 0x2000
	s_nop 0
	global_load_lds_dwordx4 v[194:195], off
	v_lshl_add_u64 v[194:195], s[40:41], 0, v[210:211]
	s_mov_b32 m0, s96
	v_lshl_add_u64 v[208:209], v[194:195], 0, s[88:89]
	global_load_lds_dwordx4 v[194:195], off
	s_mov_b32 m0, s19
	s_nop 0
	global_load_lds_dwordx4 v[208:209], off
	s_waitcnt vmcnt(9)
	s_waitcnt lgkmcnt(0)
	s_setprio 1
	s_barrier
; #define PG8_STAGE(bufoff, gbase, voff) do { _Pragma("unroll") for (int _i = 0; _i < 2; ++_i) \
;         __builtin_amdgcn_global_load_lds((const unsigned*)((const char*)(gbase) + (size_t)_i * qstep + (voff)[0]), (PG8_LAS unsigned*)(lds + (bufoff) + ldsw + _i * 8192), 16, 0, 0); } while (0)
; #define PG8_LDA(dst, b, h) do { _Pragma("unroll") for (int m = 0; m < 4; ++m) _Pragma("unroll") for (int k = 0; k < 2; ++k) dst[m][k] = *(const PG8_LAS bf16x8*)(lds + PG8_SA(b, h) + aoff + m * 2048 + k * 1024); } while (0)
; #define PG8_LDB(dst, b, h) do { _Pragma("unroll") for (int n = 0; n < 2; ++n) _Pragma("unroll") for (int k = 0; k < 2; ++k) dst[n][k] = *(const PG8_LAS bf16x8*)(lds + PG8_SB(b, h) + boff + n * 2048 + k * 1024); } while (0)
; #define PG8_MMA(ai, bj, At, Bt) do { __builtin_amdgcn_s_setprio(1); _Pragma("unroll") for (int m = 0; m < 4; ++m) _Pragma("unroll") for (int n = 0; n < 2; ++n) _Pragma("unroll") for (int k = 0; k < 2; ++k) \
;         acc[ai][bj][m][n] = __builtin_amdgcn_mfma_f32_16x16x32_bf16(Bt[n][k], At[m][k], acc[ai][bj][m][n], 0, 0, 0); __builtin_amdgcn_s_setprio(0); } while (0)
; #define PG8_WAIT_V89() do { if constexpr (SLIVER) PG8_WAIT_V(9); else PG8_WAIT_V(8); } while (0)
; #define PG8_STAGE_S(b, gbase) do { if constexpr (SLIVER) __builtin_amdgcn_global_load_lds((const unsigned*)((const char*)(gbase) + voffS), (PG8_LAS unsigned*)(lds + STAGE_BYTES + (b) * 2048 + wid * 256), 4, 0, 0); } while (0)
; #define PG8_WAIT_L(n) asm volatile("s_waitcnt lgkmcnt(" #n ")" ::: "memory")
; #define PG8_BAR __builtin_amdgcn_s_barrier()
; #define PG8_SCHED __builtin_amdgcn_sched_barrier(0)
; template <class Epi, class Sched, bool ALIGN_EPI = false, bool SP2 = false, bool SLIVER = false>
; __device__ __forceinline__ void gemm_phase(PG8_LAS unsigned char* lds, const Gemm g, const Sched& S, const Epi& E) {
;     ...
;             PG8_WAIT_V89(); PG8_WAIT_L(0); PG8_BAR; PG8_MMA(1, 0, At, B0); PG8_MMA(1, 1, At, B1); PG8_MMA_S(); PG8_BAR; PG8_SCHED;
;             PG8_LDB(B0, 1, 0); PG8_LDB(B1, 1, 1); PG8_SCHED; PG8_LDA(At, 1, 0); PG8_STAGE(PG8_SA(0, 1), a2 + hstep, voffA); PG8_STAGE_S(0, s2);
;             PG8_WAIT_V89(); PG8_WAIT_L(0); PG8_BAR; PG8_MMA(0, 0, At, B0); PG8_MMA(0, 1, At, B1); PG8_BAR; PG8_SCHED;
	v_mfma_f32_16x16x32_bf16 v[62:65], v[146:149], v[138:141], v[62:65]
	v_mfma_f32_16x16x32_bf16 v[58:61], v[154:157], v[138:141], v[58:61]
	v_mfma_f32_16x16x32_bf16 v[54:57], v[146:149], v[196:199], v[54:57]
	v_mfma_f32_16x16x32_bf16 v[50:53], v[154:157], v[196:199], v[50:53]
	v_mfma_f32_16x16x32_bf16 v[46:49], v[146:149], v[220:223], v[46:49]
	v_mfma_f32_16x16x32_bf16 v[42:45], v[154:157], v[220:223], v[42:45]
	v_mfma_f32_16x16x32_bf16 v[38:41], v[146:149], v[228:231], v[38:41]
	v_mfma_f32_16x16x32_bf16 v[34:37], v[154:157], v[228:231], v[34:37]
	v_mfma_f32_16x16x32_bf16 v[62:65], v[150:153], v[142:145], v[62:65]
	v_mfma_f32_16x16x32_bf16 v[58:61], v[158:161], v[142:145], v[58:61]
	v_mfma_f32_16x16x32_bf16 v[54:57], v[150:153], v[200:203], v[54:57]
	v_mfma_f32_16x16x32_bf16 v[50:53], v[158:161], v[200:203], v[50:53]
	v_mfma_f32_16x16x32_bf16 v[46:49], v[150:153], v[224:227], v[46:49]
	v_mfma_f32_16x16x32_bf16 v[42:45], v[158:161], v[224:227], v[42:45]
	v_mfma_f32_16x16x32_bf16 v[38:41], v[150:153], v[232:235], v[38:41]
	v_mfma_f32_16x16x32_bf16 v[34:37], v[158:161], v[232:235], v[34:37]
	s_setprio 0
	s_setprio 1
	v_mfma_f32_16x16x32_bf16 v[30:33], v[166:169], v[138:141], v[30:33]
	v_mfma_f32_16x16x32_bf16 v[26:29], v[174:177], v[138:141], v[26:29]
	v_mfma_f32_16x16x32_bf16 v[22:25], v[166:169], v[196:199], v[22:25]
	v_mfma_f32_16x16x32_bf16 v[18:21], v[174:177], v[196:199], v[18:21]
	v_mfma_f32_16x16x32_bf16 v[14:17], v[166:169], v[220:223], v[14:17]
	v_mfma_f32_16x16x32_bf16 v[10:13], v[174:177], v[220:223], v[10:13]
	v_mfma_f32_16x16x32_bf16 v[6:9], v[166:169], v[228:231], v[6:9]
	v_mfma_f32_16x16x32_bf16 v[2:5], v[174:177], v[228:231], v[2:5]
	v_mfma_f32_16x16x32_bf16 v[30:33], v[170:173], v[142:145], v[30:33]
	v_mfma_f32_16x16x32_bf16 v[26:29], v[162:165], v[142:145], v[26:29]
	v_mfma_f32_16x16x32_bf16 v[22:25], v[170:173], v[200:203], v[22:25]
	v_mfma_f32_16x16x32_bf16 v[18:21], v[162:165], v[200:203], v[18:21]
	v_mfma_f32_16x16x32_bf16 v[14:17], v[170:173], v[224:227], v[14:17]
	v_mfma_f32_16x16x32_bf16 v[10:13], v[162:165], v[224:227], v[10:13]
	v_mfma_f32_16x16x32_bf16 v[6:9], v[170:173], v[232:235], v[6:9]
	v_mfma_f32_16x16x32_bf16 v[2:5], v[162:165], v[232:235], v[2:5]
	s_setprio 0
	s_setprio 1
	s_and_b64 vcc, exec, s[52:53]
	s_cbranch_vccz .Lslv_b0
	v_mfma_f32_16x16x32_bf16 v[138:141], v[166:169], v[180:183], v[82:85]
	v_mfma_f32_16x16x32_bf16 v[142:145], v[174:177], v[180:183], v[94:97]
	v_mfma_f32_16x16x32_bf16 v[138:141], v[170:173], v[184:187], v[138:141]
	v_mfma_f32_16x16x32_bf16 v[142:145], v[162:165], v[184:187], v[142:145]
	s_branch .LBB0_502
.LBB0_500:
.Lslv_b0:
	v_mfma_f32_16x16x32_bf16 v[82:85], v[146:149], v[180:183], v[82:85]
	v_mfma_f32_16x16x32_bf16 v[138:141], v[150:153], v[184:187], v[82:85]
	v_mfma_f32_16x16x32_bf16 v[82:85], v[154:157], v[180:183], v[94:97]
	v_mfma_f32_16x16x32_bf16 v[142:145], v[158:161], v[184:187], v[82:85]
.LBB0_502:
	s_barrier
	s_setprio 0
	s_add_u32 s68, s62, s80
	s_addc_u32 s69, s63, s81
	s_add_u32 s76, s68, 0x100
	s_addc_u32 s77, s69, 0
	s_and_b64 s[68:69], s[86:87], exec
	s_cselect_b32 s69, s85, s77
	s_cselect_b32 s68, s84, s76
	s_add_i32 s76, 0, 0x18000
	v_add_u32_e32 v82, s76, v239
	s_add_i32 s77, 0, 0x1c000
	ds_read_b128 v[146:149], v82
	ds_read_b128 v[150:153], v82 offset:1024
	ds_read_b128 v[154:157], v82 offset:2048
	ds_read_b128 v[158:161], v82 offset:3072
	v_add_u32_e32 v82, s77, v239
	ds_read_b128 v[166:169], v82
	ds_read_b128 v[170:173], v82 offset:1024
	ds_read_b128 v[174:177], v82 offset:2048
	ds_read_b128 v[162:165], v82 offset:3072
	s_mov_b32 m0, s91
	v_lshl_add_u64 v[208:209], v[194:195], 0, s[24:25]
	ds_read_b128 v[82:85], v242 offset:32768
	ds_read_b128 v[94:97], v242 offset:33792
	ds_read_b128 v[180:183], v242 offset:34816
	ds_read_b128 v[184:187], v242 offset:35840
	ds_read_b128 v[196:199], v242 offset:36864
	ds_read_b128 v[200:203], v242 offset:37888
	ds_read_b128 v[220:223], v242 offset:38912
	ds_read_b128 v[224:227], v242 offset:39936
	global_load_lds_dwordx4 v[208:209], off
	v_lshl_add_u64 v[208:209], v[194:195], 0, s[14:15]
	s_mov_b32 m0, s92
	s_nop 0
	global_load_lds_dwordx4 v[208:209], off
	v_lshl_add_u64 v[208:209], s[68:69], 0, v[214:215]
	s_mov_b32 m0, s93
	s_nop 0
	global_load_lds_dword v[208:209], off
	s_waitcnt vmcnt(9)
	s_waitcnt lgkmcnt(0)
	s_setprio 1
	s_barrier
; #define PG8_SB(B) __builtin_amdgcn_rcpf(1.f + expneg(B))
; #define PG8_SB(B) __builtin_amdgcn_rcpf(1.f + expneg(B))
; #define PG8_STAGE(bufoff, gbase, voff) do { _Pragma("unroll") for (int _i = 0; _i < 2; ++_i) \
;         __builtin_amdgcn_global_load_lds((const unsigned*)((const char*)(gbase) + (size_t)_i * qstep + (voff)[0]), (PG8_LAS unsigned*)(lds + (bufoff) + ldsw + _i * 8192), 16, 0, 0); } while (0)
; #define PG8_LDA(dst, b, h) do { _Pragma("unroll") for (int m = 0; m < 4; ++m) _Pragma("unroll") for (int k = 0; k < 2; ++k) dst[m][k] = *(const PG8_LAS bf16x8*)(lds + PG8_SA(b, h) + aoff + m * 2048 + k * 1024); } while (0)
; #define PG8_MMA(ai, bj, At, Bt) do { __builtin_amdgcn_s_setprio(1); _Pragma("unroll") for (int m = 0; m < 4; ++m) _Pragma("unroll") for (int n = 0; n < 2; ++n) _Pragma("unroll") for (int k = 0; k < 2; ++k) \
;         acc[ai][bj][m][n] = __builtin_amdgcn_mfma_f32_16x16x32_bf16(Bt[n][k], At[m][k], acc[ai][bj][m][n], 0, 0, 0); __builtin_amdgcn_s_setprio(0); } while (0)
; #define PG8_WAIT_V89() do { if constexpr (SLIVER) PG8_WAIT_V(9); else PG8_WAIT_V(8); } while (0)
; #define PG8_LDS_S(b) do { if constexpr (SLIVER) { Sf[0] = *(const PG8_LAS bf16x8*)(lds + STAGE_BYTES + (b) * 2048 + soff0); Sf[1] = *(const PG8_LAS bf16x8*)(lds + STAGE_BYTES + (b) * 2048 + (soff0 ^ 64)); } } while (0)
; #define PG8_WAIT_L(n) asm volatile("s_waitcnt lgkmcnt(" #n ")" ::: "memory")
; #define PG8_BAR __builtin_amdgcn_s_barrier()
; #define PG8_SCHED __builtin_amdgcn_sched_barrier(0)
; template <class Epi, class Sched, bool ALIGN_EPI = false, bool SP2 = false, bool SLIVER = false>
; __device__ __forceinline__ void gemm_phase(PG8_LAS unsigned char* lds, const Gemm g, const Sched& S, const Epi& E) {
;     ...
;             PG8_WAIT_V89(); PG8_WAIT_L(0); PG8_BAR; PG8_MMA(0, 0, At, B0); PG8_MMA(0, 1, At, B1); PG8_BAR; PG8_SCHED;
;             PG8_LDA(At, 1, 1); PG8_LDS_S(1); PG8_STAGE(PG8_SB(1, 0), b3, voffB); PG8_STAGE(PG8_SB(1, 1), b3 + hstep, voffB); PG8_STAGE(PG8_SA(1, 0), a3, voffA);
;             PG8_WAIT_V89(); PG8_WAIT_L(0); PG8_BAR; PG8_MMA(1, 0, At, B0); PG8_MMA(1, 1, At, B1); PG8_MMA_S(); PG8_BAR; PG8_SCHED;
	v_mfma_f32_16x16x32_bf16 v[134:137], v[146:149], v[82:85], v[134:137]
	v_mfma_f32_16x16x32_bf16 v[130:133], v[154:157], v[82:85], v[130:133]
	v_mfma_f32_16x16x32_bf16 v[126:129], v[146:149], v[180:183], v[126:129]
	v_mfma_f32_16x16x32_bf16 v[122:125], v[154:157], v[180:183], v[122:125]
	v_mfma_f32_16x16x32_bf16 v[118:121], v[146:149], v[196:199], v[118:121]
	v_mfma_f32_16x16x32_bf16 v[114:117], v[154:157], v[196:199], v[114:117]
	v_mfma_f32_16x16x32_bf16 v[110:113], v[146:149], v[220:223], v[110:113]
	v_mfma_f32_16x16x32_bf16 v[106:109], v[154:157], v[220:223], v[106:109]
	v_mfma_f32_16x16x32_bf16 v[134:137], v[150:153], v[94:97], v[134:137]
	v_mfma_f32_16x16x32_bf16 v[130:133], v[158:161], v[94:97], v[130:133]
	v_mfma_f32_16x16x32_bf16 v[126:129], v[150:153], v[184:187], v[126:129]
	v_mfma_f32_16x16x32_bf16 v[122:125], v[158:161], v[184:187], v[122:125]
	v_mfma_f32_16x16x32_bf16 v[118:121], v[150:153], v[200:203], v[118:121]
	v_mfma_f32_16x16x32_bf16 v[114:117], v[158:161], v[200:203], v[114:117]
	v_mfma_f32_16x16x32_bf16 v[110:113], v[150:153], v[224:227], v[110:113]
	v_mfma_f32_16x16x32_bf16 v[106:109], v[158:161], v[224:227], v[106:109]
	s_setprio 0
	s_setprio 1
	v_mfma_f32_16x16x32_bf16 v[102:105], v[166:169], v[82:85], v[102:105]
	v_mfma_f32_16x16x32_bf16 v[82:85], v[174:177], v[82:85], v[98:101]
	v_mfma_f32_16x16x32_bf16 v[98:101], v[162:165], v[94:97], v[82:85]
	v_mfma_f32_16x16x32_bf16 v[82:85], v[166:169], v[180:183], v[90:93]
	v_mfma_f32_16x16x32_bf16 v[90:93], v[170:173], v[184:187], v[82:85]
	v_mfma_f32_16x16x32_bf16 v[82:85], v[174:177], v[180:183], v[86:89]
	v_mfma_f32_16x16x32_bf16 v[78:81], v[166:169], v[196:199], v[78:81]
	v_mfma_f32_16x16x32_bf16 v[74:77], v[174:177], v[196:199], v[74:77]
	v_mfma_f32_16x16x32_bf16 v[70:73], v[166:169], v[220:223], v[70:73]
	v_mfma_f32_16x16x32_bf16 v[66:69], v[174:177], v[220:223], v[66:69]
	v_mfma_f32_16x16x32_bf16 v[102:105], v[170:173], v[94:97], v[102:105]
	v_mfma_f32_16x16x32_bf16 v[86:89], v[162:165], v[184:187], v[82:85]
	v_mfma_f32_16x16x32_bf16 v[78:81], v[170:173], v[200:203], v[78:81]
	v_mfma_f32_16x16x32_bf16 v[74:77], v[162:165], v[200:203], v[74:77]
	v_mfma_f32_16x16x32_bf16 v[70:73], v[170:173], v[224:227], v[70:73]
	v_mfma_f32_16x16x32_bf16 v[66:69], v[162:165], v[224:227], v[66:69]
	s_barrier
	s_setprio 0
	s_add_i32 s68, 0, 0x20800
	v_add_u32_e32 v178, s68, v240
	v_add_u32_e32 v184, s68, v241
	s_add_i32 s68, s76, s95
	v_lshl_add_u64 v[208:209], v[192:193], 0, s[26:27]
	s_mov_b32 m0, s68
	ds_read_b128 v[82:85], v242 offset:49152
	ds_read_b128 v[94:97], v242 offset:50176
	ds_read_b128 v[196:199], v242 offset:51200
	ds_read_b128 v[200:203], v242 offset:52224
	ds_read_b128 v[220:223], v242 offset:53248
	ds_read_b128 v[224:227], v242 offset:54272
	ds_read_b128 v[228:231], v242 offset:55296
	ds_read_b128 v[232:235], v242 offset:56320
	ds_read_b128 v[180:183], v178
	ds_read_b128 v[184:187], v184
	global_load_lds_dwordx4 v[208:209], off
	v_lshl_add_u64 v[208:209], v[192:193], 0, s[72:73]
	s_add_i32 m0, s68, 0x2000
	s_add_i32 s68, s77, s95
	global_load_lds_dwordx4 v[208:209], off
	v_lshl_add_u64 v[208:209], v[192:193], 0, s[34:35]
	s_mov_b32 m0, s68
	s_mov_b64 s[76:77], 0x120080
	global_load_lds_dwordx4 v[208:209], off
	v_lshl_add_u64 v[192:193], v[192:193], 0, s[76:77]
	s_add_i32 m0, s68, 0x2000
	s_nop 0
	global_load_lds_dwordx4 v[192:193], off
	v_lshl_add_u64 v[192:193], v[194:195], 0, s[26:27]
	s_mov_b32 m0, s97
	s_nop 0
	global_load_lds_dwordx4 v[192:193], off
	v_lshl_add_u64 v[192:193], v[194:195], 0, s[72:73]
	s_mov_b32 m0, s18
	s_nop 0
	global_load_lds_dwordx4 v[192:193], off
	s_waitcnt vmcnt(9)
	s_waitcnt lgkmcnt(0)
	s_setprio 1
	s_barrier
	v_mfma_f32_16x16x32_bf16 v[62:65], v[146:149], v[82:85], v[62:65]
	v_mfma_f32_16x16x32_bf16 v[58:61], v[154:157], v[82:85], v[58:61]
	v_mfma_f32_16x16x32_bf16 v[54:57], v[146:149], v[196:199], v[54:57]
	v_mfma_f32_16x16x32_bf16 v[50:53], v[154:157], v[196:199], v[50:53]
	v_mfma_f32_16x16x32_bf16 v[46:49], v[146:149], v[220:223], v[46:49]
	v_mfma_f32_16x16x32_bf16 v[42:45], v[154:157], v[220:223], v[42:45]
	v_mfma_f32_16x16x32_bf16 v[38:41], v[146:149], v[228:231], v[38:41]
	v_mfma_f32_16x16x32_bf16 v[34:37], v[154:157], v[228:231], v[34:37]
	v_mfma_f32_16x16x32_bf16 v[62:65], v[150:153], v[94:97], v[62:65]
	v_mfma_f32_16x16x32_bf16 v[58:61], v[158:161], v[94:97], v[58:61]
	v_mfma_f32_16x16x32_bf16 v[54:57], v[150:153], v[200:203], v[54:57]
	v_mfma_f32_16x16x32_bf16 v[50:53], v[158:161], v[200:203], v[50:53]
	v_mfma_f32_16x16x32_bf16 v[46:49], v[150:153], v[224:227], v[46:49]
	v_mfma_f32_16x16x32_bf16 v[42:45], v[158:161], v[224:227], v[42:45]
	v_mfma_f32_16x16x32_bf16 v[38:41], v[150:153], v[232:235], v[38:41]
	v_mfma_f32_16x16x32_bf16 v[34:37], v[158:161], v[232:235], v[34:37]
	s_setprio 0
	s_setprio 1
	v_mfma_f32_16x16x32_bf16 v[30:33], v[166:169], v[82:85], v[30:33]
	v_mfma_f32_16x16x32_bf16 v[26:29], v[174:177], v[82:85], v[26:29]
	v_mfma_f32_16x16x32_bf16 v[22:25], v[166:169], v[196:199], v[22:25]
	v_mfma_f32_16x16x32_bf16 v[18:21], v[174:177], v[196:199], v[18:21]
	v_mfma_f32_16x16x32_bf16 v[14:17], v[166:169], v[220:223], v[14:17]
	v_mfma_f32_16x16x32_bf16 v[10:13], v[174:177], v[220:223], v[10:13]
	v_mfma_f32_16x16x32_bf16 v[6:9], v[166:169], v[228:231], v[6:9]
	v_mfma_f32_16x16x32_bf16 v[2:5], v[174:177], v[228:231], v[2:5]
	v_mfma_f32_16x16x32_bf16 v[30:33], v[170:173], v[94:97], v[30:33]
	v_mfma_f32_16x16x32_bf16 v[26:29], v[162:165], v[94:97], v[26:29]
	v_mfma_f32_16x16x32_bf16 v[22:25], v[170:173], v[200:203], v[22:25]
	v_mfma_f32_16x16x32_bf16 v[18:21], v[162:165], v[200:203], v[18:21]
	v_mfma_f32_16x16x32_bf16 v[14:17], v[170:173], v[224:227], v[14:17]
	v_mfma_f32_16x16x32_bf16 v[10:13], v[162:165], v[224:227], v[10:13]
	v_mfma_f32_16x16x32_bf16 v[6:9], v[170:173], v[232:235], v[6:9]
	v_mfma_f32_16x16x32_bf16 v[2:5], v[162:165], v[232:235], v[2:5]
	s_setprio 0
	s_setprio 1
	s_and_b64 vcc, exec, s[52:53]
	s_cbranch_vccz .Lslv_c0
	v_mfma_f32_16x16x32_bf16 v[82:85], v[166:169], v[180:183], v[138:141]
	v_mfma_f32_16x16x32_bf16 v[94:97], v[174:177], v[180:183], v[142:145]
	v_mfma_f32_16x16x32_bf16 v[82:85], v[170:173], v[184:187], v[82:85]
	v_mfma_f32_16x16x32_bf16 v[94:97], v[162:165], v[184:187], v[94:97]
	s_branch .LBB0_497
.LBB0_504:
.Lslv_c0:
	v_mfma_f32_16x16x32_bf16 v[82:85], v[146:149], v[180:183], v[138:141]
	v_mfma_f32_16x16x32_bf16 v[94:97], v[154:157], v[180:183], v[142:145]
	v_mfma_f32_16x16x32_bf16 v[82:85], v[150:153], v[184:187], v[82:85]
	v_mfma_f32_16x16x32_bf16 v[94:97], v[158:161], v[184:187], v[94:97]
	s_branch .LBB0_497

; #define PG8_SB(B) __builtin_amdgcn_rcpf(1.f + expneg(B))
; #define PG8_SB(B) __builtin_amdgcn_rcpf(1.f + expneg(B))
; #define PG8_STAGE(bufoff, gbase, voff) do { _Pragma("unroll") for (int _i = 0; _i < 2; ++_i) \
;         __builtin_amdgcn_global_load_lds((const unsigned*)((const char*)(gbase) + (size_t)_i * qstep + (voff)[0]), (PG8_LAS unsigned*)(lds + (bufoff) + ldsw + _i * 8192), 16, 0, 0); } while (0)
; #define PG8_LDA(dst, b, h) do { _Pragma("unroll") for (int m = 0; m < 4; ++m) _Pragma("unroll") for (int k = 0; k < 2; ++k) dst[m][k] = *(const PG8_LAS bf16x8*)(lds + PG8_SA(b, h) + aoff + m * 2048 + k * 1024); } while (0)
; #define PG8_LDB(dst, b, h) do { _Pragma("unroll") for (int n = 0; n < 2; ++n) _Pragma("unroll") for (int k = 0; k < 2; ++k) dst[n][k] = *(const PG8_LAS bf16x8*)(lds + PG8_SB(b, h) + boff + n * 2048 + k * 1024); } while (0)
; #define PG8_WAIT_V89() do { if constexpr (SLIVER) PG8_WAIT_V(9); else PG8_WAIT_V(8); } while (0)
; #define PG8_STAGE_S(b, gbase) do { if constexpr (SLIVER) __builtin_amdgcn_global_load_lds((const unsigned*)((const char*)(gbase) + voffS), (PG8_LAS unsigned*)(lds + STAGE_BYTES + (b) * 2048 + wid * 256), 4, 0, 0); } while (0)
; template <class Epi, class Sched, bool ALIGN_EPI = false, bool SP2 = false, bool SLIVER = false>
; __device__ __forceinline__ void gemm_phase(PG8_LAS unsigned char* lds, const Gemm g, const Sched& S, const Epi& E) {
;     ...
;         for (int t = 0; t < nt; t += 2) {
;             const bool last = (t == nt - 2);
;             const char* a1 = cA + (size_t)(t + 1) * kstep;
;             const char* a2 = last ? nA : cA + (size_t)(t + 2) * kstep; const char* b2 = last ? nB : cB + (size_t)(t + 2) * kstep;
;             const char* a3 = a2 + kstep; const char* b3 = b2 + kstep;
;             const char* s1 = cS + (size_t)(t + 1) * kstep; const char* s2 = last ? nS : cS + (size_t)(t + 2) * kstep;
;             if (last && has_next) S.a_ready(nxt);
;             if constexpr (SP2) {
;             PG8_LDB(B0, 0, 0); PG8_LDB(B1, 0, 1); PG8_SCHED; PG8_LDA(At, 0, 0); PG8_STAGE(PG8_SA(1, 1), a1 + hstep, voffA); PG8_STAGE_S(1, s1);
;             PG8_WAIT_V89(); PG8_WAIT_L(0); PG8_BAR; PG8_MMA(0, 0, At, B0); PG8_MMA(0, 1, At, B1); PG8_BAR; PG8_SCHED;
;             PG8_LDA(At, 0, 1); PG8_LDS_S(0); PG8_STAGE(PG8_SB(0, 0), b2, voffB); PG8_STAGE(PG8_SB(0, 1), b2 + hstep, voffB); PG8_STAGE(PG8_SA(0, 0), a2, voffA);
.LBB0_598:
	s_add_u32 s40, s92, s62
	s_addc_u32 s41, s93, s63
	s_add_u32 s77, s40, 0x100
	s_addc_u32 s78, s41, 0
	s_add_u32 s83, s68, s62
	s_addc_u32 s79, s69, s63
	s_add_i32 s96, 0, 0x10000
	s_cmpk_eq_i32 s62, 0xf00
	s_cselect_b64 s[80:81], -1, 0
	s_and_b64 s[40:41], s[80:81], exec
	s_cselect_b32 s41, s12, s78
	s_cselect_b32 s40, s13, s77
	v_add_u32_e32 v138, s96, v212
	s_cselect_b32 s79, s17, s79
	s_cselect_b32 s78, s55, s83
	s_add_i32 s77, 0, 0x14000
	ds_read_b128 v[146:149], v138
	ds_read_b128 v[150:153], v138 offset:1024
	ds_read_b128 v[154:157], v138 offset:2048
	ds_read_b128 v[158:161], v138 offset:3072
	v_add_u32_e32 v138, s77, v212
	ds_read_b128 v[166:169], v138
	ds_read_b128 v[170:173], v138 offset:1024
	ds_read_b128 v[174:177], v138 offset:2048
	ds_read_b128 v[162:165], v138 offset:3072
	v_lshl_add_u64 v[202:203], v[200:201], 0, s[62:63]
	v_lshl_add_u64 v[208:209], v[202:203], 0, s[30:31]
	s_add_i32 m0, s85, 0xc000
	ds_read_b128 v[138:141], v215
	ds_read_b128 v[142:145], v215 offset:1024
	ds_read_b128 v[180:183], v215 offset:2048
	ds_read_b128 v[184:187], v215 offset:3072
	ds_read_b128 v[216:219], v215 offset:4096
	ds_read_b128 v[220:223], v215 offset:5120
	ds_read_b128 v[224:227], v215 offset:6144
	ds_read_b128 v[228:231], v215 offset:7168
	global_load_lds_dwordx4 v[208:209], off
	v_lshl_add_u64 v[202:203], v[202:203], 0, s[34:35]
	s_add_i32 m0, s85, 0xe000
	s_nop 0
	global_load_lds_dwordx4 v[202:203], off
	v_lshl_add_u64 v[202:203], v[198:199], 0, s[62:63]
	s_add_i32 m0, s45, 0x20800
	s_nop 0
	global_load_lds_dword v[202:203], off
	s_waitcnt vmcnt(9)
	s_waitcnt lgkmcnt(0)
	s_setprio 1
	s_barrier
	v_mfma_f32_16x16x32_bf16 v[134:137], v[146:149], v[138:141], v[134:137]
	v_mfma_f32_16x16x32_bf16 v[130:133], v[154:157], v[138:141], v[130:133]
	v_mfma_f32_16x16x32_bf16 v[118:121], v[146:149], v[180:183], v[118:121]
	v_mfma_f32_16x16x32_bf16 v[114:117], v[154:157], v[180:183], v[114:117]
	v_mfma_f32_16x16x32_bf16 v[102:105], v[146:149], v[216:219], v[102:105]
	v_mfma_f32_16x16x32_bf16 v[98:101], v[154:157], v[216:219], v[98:101]
	v_mfma_f32_16x16x32_bf16 v[86:89], v[146:149], v[224:227], v[86:89]
	v_mfma_f32_16x16x32_bf16 v[82:85], v[154:157], v[224:227], v[82:85]
	v_mfma_f32_16x16x32_bf16 v[134:137], v[150:153], v[142:145], v[134:137]
	v_mfma_f32_16x16x32_bf16 v[130:133], v[158:161], v[142:145], v[130:133]
	v_mfma_f32_16x16x32_bf16 v[118:121], v[150:153], v[184:187], v[118:121]
	v_mfma_f32_16x16x32_bf16 v[114:117], v[158:161], v[184:187], v[114:117]
	v_mfma_f32_16x16x32_bf16 v[102:105], v[150:153], v[220:223], v[102:105]
	v_mfma_f32_16x16x32_bf16 v[98:101], v[158:161], v[220:223], v[98:101]
	v_mfma_f32_16x16x32_bf16 v[86:89], v[150:153], v[228:231], v[86:89]
	v_mfma_f32_16x16x32_bf16 v[82:85], v[158:161], v[228:231], v[82:85]
	s_setprio 0
	s_setprio 1
	v_mfma_f32_16x16x32_bf16 v[126:129], v[166:169], v[138:141], v[126:129]
	v_mfma_f32_16x16x32_bf16 v[122:125], v[174:177], v[138:141], v[122:125]
	v_mfma_f32_16x16x32_bf16 v[110:113], v[166:169], v[180:183], v[110:113]
	v_mfma_f32_16x16x32_bf16 v[106:109], v[174:177], v[180:183], v[106:109]
	v_mfma_f32_16x16x32_bf16 v[94:97], v[166:169], v[216:219], v[94:97]
	v_mfma_f32_16x16x32_bf16 v[90:93], v[174:177], v[216:219], v[90:93]
	v_mfma_f32_16x16x32_bf16 v[78:81], v[166:169], v[224:227], v[78:81]
	v_mfma_f32_16x16x32_bf16 v[74:77], v[174:177], v[224:227], v[74:77]
	v_mfma_f32_16x16x32_bf16 v[126:129], v[170:173], v[142:145], v[126:129]
	v_mfma_f32_16x16x32_bf16 v[122:125], v[162:165], v[142:145], v[122:125]
	v_mfma_f32_16x16x32_bf16 v[110:113], v[170:173], v[184:187], v[110:113]
	v_mfma_f32_16x16x32_bf16 v[106:109], v[162:165], v[184:187], v[106:109]
	v_mfma_f32_16x16x32_bf16 v[94:97], v[170:173], v[220:223], v[94:97]
	v_mfma_f32_16x16x32_bf16 v[90:93], v[162:165], v[220:223], v[90:93]
	v_mfma_f32_16x16x32_bf16 v[78:81], v[170:173], v[228:231], v[78:81]
	v_mfma_f32_16x16x32_bf16 v[74:77], v[162:165], v[228:231], v[74:77]
	s_barrier
	s_setprio 0
	s_add_i32 s83, 0, 0x20000
	v_lshl_add_u64 v[202:203], s[78:79], 0, v[190:191]
	s_add_i32 s78, s96, s18
	v_add_u32_e32 v178, s83, v213
	v_add_u32_e32 v184, s83, v214
	s_mov_b32 m0, s78
	ds_read_b128 v[138:141], v215 offset:16384
	ds_read_b128 v[142:145], v215 offset:17408
	ds_read_b128 v[216:219], v215 offset:18432
	ds_read_b128 v[220:223], v215 offset:19456
	ds_read_b128 v[224:227], v215 offset:20480
	ds_read_b128 v[228:231], v215 offset:21504
	ds_read_b128 v[232:235], v215 offset:22528
	ds_read_b128 v[240:243], v215 offset:23552
	ds_read_b128 v[180:183], v178
	ds_read_b128 v[184:187], v184
	global_load_lds_dwordx4 v[202:203], off
	v_lshl_add_u64 v[208:209], v[202:203], 0, s[20:21]
	s_add_i32 m0, s78, 0x2000
	s_add_i32 s77, s77, s18
	global_load_lds_dwordx4 v[208:209], off
	v_lshl_add_u64 v[208:209], v[202:203], 0, s[22:23]
	s_mov_b32 m0, s77
	v_lshl_add_u64 v[210:211], s[40:41], 0, v[188:189]
	global_load_lds_dwordx4 v[208:209], off
	v_lshl_add_u64 v[208:209], v[202:203], 0, s[24:25]
	s_add_i32 m0, s77, 0x2000
	s_nop 0
	global_load_lds_dwordx4 v[208:209], off
	s_mov_b32 m0, s85
	v_lshl_add_u64 v[208:209], v[210:211], 0, s[20:21]
	global_load_lds_dwordx4 v[210:211], off
	s_mov_b32 m0, s19
	s_nop 0
	global_load_lds_dwordx4 v[208:209], off
	s_waitcnt vmcnt(9)
	s_waitcnt lgkmcnt(0)
	s_setprio 1
	s_barrier
; #define PG8_STAGE(bufoff, gbase, voff) do { _Pragma("unroll") for (int _i = 0; _i < 2; ++_i) \
;         __builtin_amdgcn_global_load_lds((const unsigned*)((const char*)(gbase) + (size_t)_i * qstep + (voff)[0]), (PG8_LAS unsigned*)(lds + (bufoff) + ldsw + _i * 8192), 16, 0, 0); } while (0)
; #define PG8_LDA(dst, b, h) do { _Pragma("unroll") for (int m = 0; m < 4; ++m) _Pragma("unroll") for (int k = 0; k < 2; ++k) dst[m][k] = *(const PG8_LAS bf16x8*)(lds + PG8_SA(b, h) + aoff + m * 2048 + k * 1024); } while (0)
; #define PG8_LDB(dst, b, h) do { _Pragma("unroll") for (int n = 0; n < 2; ++n) _Pragma("unroll") for (int k = 0; k < 2; ++k) dst[n][k] = *(const PG8_LAS bf16x8*)(lds + PG8_SB(b, h) + boff + n * 2048 + k * 1024); } while (0)
; #define PG8_MMA(ai, bj, At, Bt) do { __builtin_amdgcn_s_setprio(1); _Pragma("unroll") for (int m = 0; m < 4; ++m) _Pragma("unroll") for (int n = 0; n < 2; ++n) _Pragma("unroll") for (int k = 0; k < 2; ++k) \
;         acc[ai][bj][m][n] = __builtin_amdgcn_mfma_f32_16x16x32_bf16(Bt[n][k], At[m][k], acc[ai][bj][m][n], 0, 0, 0); __builtin_amdgcn_s_setprio(0); } while (0)
; #define PG8_WAIT_V89() do { if constexpr (SLIVER) PG8_WAIT_V(9); else PG8_WAIT_V(8); } while (0)
; #define PG8_STAGE_S(b, gbase) do { if constexpr (SLIVER) __builtin_amdgcn_global_load_lds((const unsigned*)((const char*)(gbase) + voffS), (PG8_LAS unsigned*)(lds + STAGE_BYTES + (b) * 2048 + wid * 256), 4, 0, 0); } while (0)
; #define PG8_WAIT_L(n) asm volatile("s_waitcnt lgkmcnt(" #n ")" ::: "memory")
; #define PG8_BAR __builtin_amdgcn_s_barrier()
; #define PG8_SCHED __builtin_amdgcn_sched_barrier(0)
; template <class Epi, class Sched, bool ALIGN_EPI = false, bool SP2 = false, bool SLIVER = false>
; __device__ __forceinline__ void gemm_phase(PG8_LAS unsigned char* lds, const Gemm g, const Sched& S, const Epi& E) {
;     ...
;             PG8_WAIT_V89(); PG8_WAIT_L(0); PG8_BAR; PG8_MMA(1, 0, At, B0); PG8_MMA(1, 1, At, B1); PG8_MMA_S(); PG8_BAR; PG8_SCHED;
;             PG8_LDB(B0, 1, 0); PG8_LDB(B1, 1, 1); PG8_SCHED; PG8_LDA(At, 1, 0); PG8_STAGE(PG8_SA(0, 1), a2 + hstep, voffA); PG8_STAGE_S(0, s2);
;             PG8_WAIT_V89(); PG8_WAIT_L(0); PG8_BAR; PG8_MMA(0, 0, At, B0); PG8_MMA(0, 1, At, B1); PG8_BAR; PG8_SCHED;
	v_mfma_f32_16x16x32_bf16 v[70:73], v[146:149], v[138:141], v[70:73]
	v_mfma_f32_16x16x32_bf16 v[66:69], v[154:157], v[138:141], v[66:69]
	v_mfma_f32_16x16x32_bf16 v[54:57], v[146:149], v[216:219], v[54:57]
	v_mfma_f32_16x16x32_bf16 v[50:53], v[154:157], v[216:219], v[50:53]
	v_mfma_f32_16x16x32_bf16 v[38:41], v[146:149], v[224:227], v[38:41]
	v_mfma_f32_16x16x32_bf16 v[34:37], v[154:157], v[224:227], v[34:37]
	v_mfma_f32_16x16x32_bf16 v[22:25], v[146:149], v[232:235], v[22:25]
	v_mfma_f32_16x16x32_bf16 v[18:21], v[154:157], v[232:235], v[18:21]
	v_mfma_f32_16x16x32_bf16 v[70:73], v[150:153], v[142:145], v[70:73]
	v_mfma_f32_16x16x32_bf16 v[66:69], v[158:161], v[142:145], v[66:69]
	v_mfma_f32_16x16x32_bf16 v[54:57], v[150:153], v[220:223], v[54:57]
	v_mfma_f32_16x16x32_bf16 v[50:53], v[158:161], v[220:223], v[50:53]
	v_mfma_f32_16x16x32_bf16 v[38:41], v[150:153], v[228:231], v[38:41]
	v_mfma_f32_16x16x32_bf16 v[34:37], v[158:161], v[228:231], v[34:37]
	v_mfma_f32_16x16x32_bf16 v[22:25], v[150:153], v[240:243], v[22:25]
	v_mfma_f32_16x16x32_bf16 v[18:21], v[158:161], v[240:243], v[18:21]
	s_setprio 0
	s_setprio 1
	v_mfma_f32_16x16x32_bf16 v[62:65], v[166:169], v[138:141], v[62:65]
	v_mfma_f32_16x16x32_bf16 v[58:61], v[174:177], v[138:141], v[58:61]
	v_mfma_f32_16x16x32_bf16 v[46:49], v[166:169], v[216:219], v[46:49]
	v_mfma_f32_16x16x32_bf16 v[42:45], v[174:177], v[216:219], v[42:45]
	v_mfma_f32_16x16x32_bf16 v[30:33], v[166:169], v[224:227], v[30:33]
	v_mfma_f32_16x16x32_bf16 v[26:29], v[174:177], v[224:227], v[26:29]
	v_mfma_f32_16x16x32_bf16 v[14:17], v[166:169], v[232:235], v[14:17]
	v_mfma_f32_16x16x32_bf16 v[10:13], v[174:177], v[232:235], v[10:13]
	v_mfma_f32_16x16x32_bf16 v[62:65], v[170:173], v[142:145], v[62:65]
	v_mfma_f32_16x16x32_bf16 v[58:61], v[162:165], v[142:145], v[58:61]
	v_mfma_f32_16x16x32_bf16 v[46:49], v[170:173], v[220:223], v[46:49]
	v_mfma_f32_16x16x32_bf16 v[42:45], v[162:165], v[220:223], v[42:45]
	v_mfma_f32_16x16x32_bf16 v[30:33], v[170:173], v[228:231], v[30:33]
	v_mfma_f32_16x16x32_bf16 v[26:29], v[162:165], v[228:231], v[26:29]
	v_mfma_f32_16x16x32_bf16 v[14:17], v[170:173], v[240:243], v[14:17]
	v_mfma_f32_16x16x32_bf16 v[10:13], v[162:165], v[240:243], v[10:13]
	s_setprio 0
	s_setprio 1
	s_and_b64 vcc, exec, s[52:53]
	s_cbranch_vccz .Lslv_b1
	v_mfma_f32_16x16x32_bf16 v[138:141], v[166:169], v[180:183], v[6:9]
	v_mfma_f32_16x16x32_bf16 v[142:145], v[174:177], v[180:183], v[2:5]
	v_mfma_f32_16x16x32_bf16 v[138:141], v[170:173], v[184:187], v[138:141]
	v_mfma_f32_16x16x32_bf16 v[142:145], v[162:165], v[184:187], v[142:145]
	s_branch .LBB0_602
.LBB0_600:
.Lslv_b1:
	v_mfma_f32_16x16x32_bf16 v[6:9], v[146:149], v[180:183], v[6:9]
	v_mfma_f32_16x16x32_bf16 v[2:5], v[154:157], v[180:183], v[2:5]
	v_mfma_f32_16x16x32_bf16 v[138:141], v[150:153], v[184:187], v[6:9]
	v_mfma_f32_16x16x32_bf16 v[142:145], v[158:161], v[184:187], v[2:5]
.LBB0_602:
	s_barrier
	s_setprio 0
	s_add_u32 s77, s94, s62
	s_addc_u32 s78, s95, s63
	s_add_u32 s77, s77, 0x100
	s_addc_u32 s83, s78, 0
	s_and_b64 s[78:79], s[80:81], exec
	s_cselect_b32 s79, s66, s83
	s_cselect_b32 s78, s67, s77
	s_add_i32 s77, 0, 0x18000
	v_add_u32_e32 v2, s77, v212
	s_add_i32 s80, 0, 0x1c000
	ds_read_b128 v[146:149], v2
	ds_read_b128 v[150:153], v2 offset:1024
	ds_read_b128 v[154:157], v2 offset:2048
	ds_read_b128 v[158:161], v2 offset:3072
	v_add_u32_e32 v2, s80, v212
	ds_read_b128 v[166:169], v2
	ds_read_b128 v[170:173], v2 offset:1024
	ds_read_b128 v[174:177], v2 offset:2048
	ds_read_b128 v[162:165], v2 offset:3072
	s_mov_b32 m0, s49
	v_lshl_add_u64 v[208:209], v[210:211], 0, s[22:23]
	ds_read_b128 v[2:5], v215 offset:32768
	ds_read_b128 v[6:9], v215 offset:33792
	ds_read_b128 v[180:183], v215 offset:34816
	ds_read_b128 v[184:187], v215 offset:35840
	ds_read_b128 v[216:219], v215 offset:36864
	ds_read_b128 v[220:223], v215 offset:37888
	ds_read_b128 v[224:227], v215 offset:38912
	ds_read_b128 v[228:231], v215 offset:39936
	global_load_lds_dwordx4 v[208:209], off
	v_lshl_add_u64 v[208:209], v[210:211], 0, s[24:25]
	s_mov_b32 m0, s50
	s_nop 0
	global_load_lds_dwordx4 v[208:209], off
	v_lshl_add_u64 v[208:209], s[78:79], 0, v[192:193]
	s_mov_b32 m0, s51
	s_nop 0
	global_load_lds_dword v[208:209], off
	s_waitcnt vmcnt(9)
	s_waitcnt lgkmcnt(0)
	s_setprio 1
	s_barrier
; #define PG8_SB(B) __builtin_amdgcn_rcpf(1.f + expneg(B))
; #define PG8_SB(B) __builtin_amdgcn_rcpf(1.f + expneg(B))
; #define PG8_STAGE(bufoff, gbase, voff) do { _Pragma("unroll") for (int _i = 0; _i < 2; ++_i) \
;         __builtin_amdgcn_global_load_lds((const unsigned*)((const char*)(gbase) + (size_t)_i * qstep + (voff)[0]), (PG8_LAS unsigned*)(lds + (bufoff) + ldsw + _i * 8192), 16, 0, 0); } while (0)
; #define PG8_LDA(dst, b, h) do { _Pragma("unroll") for (int m = 0; m < 4; ++m) _Pragma("unroll") for (int k = 0; k < 2; ++k) dst[m][k] = *(const PG8_LAS bf16x8*)(lds + PG8_SA(b, h) + aoff + m * 2048 + k * 1024); } while (0)
; #define PG8_MMA(ai, bj, At, Bt) do { __builtin_amdgcn_s_setprio(1); _Pragma("unroll") for (int m = 0; m < 4; ++m) _Pragma("unroll") for (int n = 0; n < 2; ++n) _Pragma("unroll") for (int k = 0; k < 2; ++k) \
;         acc[ai][bj][m][n] = __builtin_amdgcn_mfma_f32_16x16x32_bf16(Bt[n][k], At[m][k], acc[ai][bj][m][n], 0, 0, 0); __builtin_amdgcn_s_setprio(0); } while (0)
; #define PG8_WAIT_V89() do { if constexpr (SLIVER) PG8_WAIT_V(9); else PG8_WAIT_V(8); } while (0)
; #define PG8_LDS_S(b) do { if constexpr (SLIVER) { Sf[0] = *(const PG8_LAS bf16x8*)(lds + STAGE_BYTES + (b) * 2048 + soff0); Sf[1] = *(const PG8_LAS bf16x8*)(lds + STAGE_BYTES + (b) * 2048 + (soff0 ^ 64)); } } while (0)
; #define PG8_WAIT_L(n) asm volatile("s_waitcnt lgkmcnt(" #n ")" ::: "memory")
; #define PG8_BAR __builtin_amdgcn_s_barrier()
; #define PG8_SCHED __builtin_amdgcn_sched_barrier(0)
; template <class Epi, class Sched, bool ALIGN_EPI = false, bool SP2 = false, bool SLIVER = false>
; __device__ __forceinline__ void gemm_phase(PG8_LAS unsigned char* lds, const Gemm g, const Sched& S, const Epi& E) {
;     ...
;             PG8_WAIT_V89(); PG8_WAIT_L(0); PG8_BAR; PG8_MMA(0, 0, At, B0); PG8_MMA(0, 1, At, B1); PG8_BAR; PG8_SCHED;
;             PG8_LDA(At, 1, 1); PG8_LDS_S(1); PG8_STAGE(PG8_SB(1, 0), b3, voffB); PG8_STAGE(PG8_SB(1, 1), b3 + hstep, voffB); PG8_STAGE(PG8_SA(1, 0), a3, voffA);
;             PG8_WAIT_V89(); PG8_WAIT_L(0); PG8_BAR; PG8_MMA(1, 0, At, B0); PG8_MMA(1, 1, At, B1); PG8_MMA_S(); PG8_BAR; PG8_SCHED;
	v_mfma_f32_16x16x32_bf16 v[134:137], v[146:149], v[2:5], v[134:137]
	v_mfma_f32_16x16x32_bf16 v[130:133], v[154:157], v[2:5], v[130:133]
	v_mfma_f32_16x16x32_bf16 v[118:121], v[146:149], v[180:183], v[118:121]
	v_mfma_f32_16x16x32_bf16 v[114:117], v[154:157], v[180:183], v[114:117]
	v_mfma_f32_16x16x32_bf16 v[102:105], v[146:149], v[216:219], v[102:105]
	v_mfma_f32_16x16x32_bf16 v[98:101], v[154:157], v[216:219], v[98:101]
	v_mfma_f32_16x16x32_bf16 v[86:89], v[146:149], v[224:227], v[86:89]
	v_mfma_f32_16x16x32_bf16 v[82:85], v[154:157], v[224:227], v[82:85]
	v_mfma_f32_16x16x32_bf16 v[134:137], v[150:153], v[6:9], v[134:137]
	v_mfma_f32_16x16x32_bf16 v[130:133], v[158:161], v[6:9], v[130:133]
	v_mfma_f32_16x16x32_bf16 v[118:121], v[150:153], v[184:187], v[118:121]
	v_mfma_f32_16x16x32_bf16 v[114:117], v[158:161], v[184:187], v[114:117]
	v_mfma_f32_16x16x32_bf16 v[102:105], v[150:153], v[220:223], v[102:105]
	v_mfma_f32_16x16x32_bf16 v[98:101], v[158:161], v[220:223], v[98:101]
	v_mfma_f32_16x16x32_bf16 v[86:89], v[150:153], v[228:231], v[86:89]
	v_mfma_f32_16x16x32_bf16 v[82:85], v[158:161], v[228:231], v[82:85]
	s_setprio 0
	s_setprio 1
	v_mfma_f32_16x16x32_bf16 v[126:129], v[166:169], v[2:5], v[126:129]
	v_mfma_f32_16x16x32_bf16 v[2:5], v[174:177], v[2:5], v[122:125]
	v_mfma_f32_16x16x32_bf16 v[122:125], v[162:165], v[6:9], v[2:5]
	v_mfma_f32_16x16x32_bf16 v[2:5], v[166:169], v[180:183], v[110:113]
	v_mfma_f32_16x16x32_bf16 v[110:113], v[170:173], v[184:187], v[2:5]
	v_mfma_f32_16x16x32_bf16 v[2:5], v[174:177], v[180:183], v[106:109]
	v_mfma_f32_16x16x32_bf16 v[106:109], v[162:165], v[184:187], v[2:5]
	v_mfma_f32_16x16x32_bf16 v[2:5], v[166:169], v[216:219], v[94:97]
	v_mfma_f32_16x16x32_bf16 v[94:97], v[170:173], v[220:223], v[2:5]
	v_mfma_f32_16x16x32_bf16 v[2:5], v[174:177], v[216:219], v[90:93]
	v_mfma_f32_16x16x32_bf16 v[90:93], v[162:165], v[220:223], v[2:5]
	v_mfma_f32_16x16x32_bf16 v[2:5], v[166:169], v[224:227], v[78:81]
	v_mfma_f32_16x16x32_bf16 v[78:81], v[170:173], v[228:231], v[2:5]
	v_mfma_f32_16x16x32_bf16 v[2:5], v[174:177], v[224:227], v[74:77]
	v_mfma_f32_16x16x32_bf16 v[126:129], v[170:173], v[6:9], v[126:129]
	v_mfma_f32_16x16x32_bf16 v[74:77], v[162:165], v[228:231], v[2:5]
	s_barrier
	s_setprio 0
	s_add_i32 s78, 0, 0x20800
	s_add_i32 s77, s77, s18
	v_add_u32_e32 v178, s78, v213
	v_add_u32_e32 v184, s78, v214
	v_lshl_add_u64 v[208:209], v[202:203], 0, s[26:27]
	s_mov_b32 m0, s77
	ds_read_b128 v[2:5], v215 offset:49152
	ds_read_b128 v[6:9], v215 offset:50176
	ds_read_b128 v[216:219], v215 offset:51200
	ds_read_b128 v[220:223], v215 offset:52224
	ds_read_b128 v[224:227], v215 offset:53248
	ds_read_b128 v[228:231], v215 offset:54272
	ds_read_b128 v[232:235], v215 offset:55296
	ds_read_b128 v[240:243], v215 offset:56320
	ds_read_b128 v[180:183], v178
	ds_read_b128 v[184:187], v184
	global_load_lds_dwordx4 v[208:209], off
	v_lshl_add_u64 v[208:209], v[202:203], 0, s[28:29]
	s_add_i32 m0, s77, 0x2000
	s_add_i32 s77, s80, s18
	global_load_lds_dwordx4 v[208:209], off
	v_lshl_add_u64 v[208:209], v[202:203], 0, s[30:31]
	s_mov_b32 m0, s77
	v_lshl_add_u64 v[202:203], v[202:203], 0, s[34:35]
	global_load_lds_dwordx4 v[208:209], off
	s_add_i32 m0, s77, 0x2000
	s_nop 0
	global_load_lds_dwordx4 v[202:203], off
	v_lshl_add_u64 v[202:203], v[210:211], 0, s[26:27]
	s_mov_b32 m0, s10
	s_nop 0
	global_load_lds_dwordx4 v[202:203], off
	v_lshl_add_u64 v[202:203], v[210:211], 0, s[28:29]
	s_mov_b32 m0, s2
	s_nop 0
	global_load_lds_dwordx4 v[202:203], off
	s_waitcnt vmcnt(9)
	s_waitcnt lgkmcnt(0)
	s_setprio 1
	s_barrier
	v_mfma_f32_16x16x32_bf16 v[70:73], v[146:149], v[2:5], v[70:73]
	v_mfma_f32_16x16x32_bf16 v[66:69], v[154:157], v[2:5], v[66:69]
	v_mfma_f32_16x16x32_bf16 v[54:57], v[146:149], v[216:219], v[54:57]
	v_mfma_f32_16x16x32_bf16 v[50:53], v[154:157], v[216:219], v[50:53]
	v_mfma_f32_16x16x32_bf16 v[38:41], v[146:149], v[224:227], v[38:41]
	v_mfma_f32_16x16x32_bf16 v[34:37], v[154:157], v[224:227], v[34:37]
	v_mfma_f32_16x16x32_bf16 v[22:25], v[146:149], v[232:235], v[22:25]
	v_mfma_f32_16x16x32_bf16 v[18:21], v[154:157], v[232:235], v[18:21]
	v_mfma_f32_16x16x32_bf16 v[70:73], v[150:153], v[6:9], v[70:73]
	v_mfma_f32_16x16x32_bf16 v[66:69], v[158:161], v[6:9], v[66:69]
	v_mfma_f32_16x16x32_bf16 v[54:57], v[150:153], v[220:223], v[54:57]
	v_mfma_f32_16x16x32_bf16 v[50:53], v[158:161], v[220:223], v[50:53]
	v_mfma_f32_16x16x32_bf16 v[38:41], v[150:153], v[228:231], v[38:41]
	v_mfma_f32_16x16x32_bf16 v[34:37], v[158:161], v[228:231], v[34:37]
	v_mfma_f32_16x16x32_bf16 v[22:25], v[150:153], v[240:243], v[22:25]
	v_mfma_f32_16x16x32_bf16 v[18:21], v[158:161], v[240:243], v[18:21]
	s_setprio 0
	s_setprio 1
	v_mfma_f32_16x16x32_bf16 v[62:65], v[166:169], v[2:5], v[62:65]
	v_mfma_f32_16x16x32_bf16 v[2:5], v[174:177], v[2:5], v[58:61]
	v_mfma_f32_16x16x32_bf16 v[58:61], v[162:165], v[6:9], v[2:5]
	v_mfma_f32_16x16x32_bf16 v[2:5], v[166:169], v[216:219], v[46:49]
	v_mfma_f32_16x16x32_bf16 v[46:49], v[170:173], v[220:223], v[2:5]
	v_mfma_f32_16x16x32_bf16 v[2:5], v[174:177], v[216:219], v[42:45]
	v_mfma_f32_16x16x32_bf16 v[42:45], v[162:165], v[220:223], v[2:5]
	v_mfma_f32_16x16x32_bf16 v[2:5], v[166:169], v[224:227], v[30:33]
	v_mfma_f32_16x16x32_bf16 v[30:33], v[170:173], v[228:231], v[2:5]
	v_mfma_f32_16x16x32_bf16 v[2:5], v[174:177], v[224:227], v[26:29]
	v_mfma_f32_16x16x32_bf16 v[26:29], v[162:165], v[228:231], v[2:5]
	v_mfma_f32_16x16x32_bf16 v[2:5], v[166:169], v[232:235], v[14:17]
	v_mfma_f32_16x16x32_bf16 v[14:17], v[170:173], v[240:243], v[2:5]
	v_mfma_f32_16x16x32_bf16 v[2:5], v[174:177], v[232:235], v[10:13]
	v_mfma_f32_16x16x32_bf16 v[62:65], v[170:173], v[6:9], v[62:65]
	v_mfma_f32_16x16x32_bf16 v[10:13], v[162:165], v[240:243], v[2:5]
	s_setprio 0
	s_setprio 1
	s_and_b64 vcc, exec, s[52:53]
	s_cbranch_vccz .Lslv_c1
	v_mfma_f32_16x16x32_bf16 v[2:5], v[166:169], v[180:183], v[138:141]
	v_mfma_f32_16x16x32_bf16 v[6:9], v[170:173], v[184:187], v[2:5]
	v_mfma_f32_16x16x32_bf16 v[2:5], v[174:177], v[180:183], v[142:145]
	v_mfma_f32_16x16x32_bf16 v[2:5], v[162:165], v[184:187], v[2:5]
	s_branch .LBB0_597
.LBB0_604:
.Lslv_c1:
	v_mfma_f32_16x16x32_bf16 v[2:5], v[146:149], v[180:183], v[138:141]
	v_mfma_f32_16x16x32_bf16 v[6:9], v[150:153], v[184:187], v[2:5]
	v_mfma_f32_16x16x32_bf16 v[2:5], v[154:157], v[180:183], v[142:145]
	v_mfma_f32_16x16x32_bf16 v[2:5], v[158:161], v[184:187], v[2:5]
	s_branch .LBB0_597

; #define PG8_SB(B) __builtin_amdgcn_rcpf(1.f + expneg(B))
; #define PG8_SB(B) __builtin_amdgcn_rcpf(1.f + expneg(B))
; #define PG8_STAGE(bufoff, gbase, voff) do { _Pragma("unroll") for (int _i = 0; _i < 2; ++_i) \
;         __builtin_amdgcn_global_load_lds((const unsigned*)((const char*)(gbase) + (size_t)_i * qstep + (voff)[0]), (PG8_LAS unsigned*)(lds + (bufoff) + ldsw + _i * 8192), 16, 0, 0); } while (0)
; #define PG8_LDA(dst, b, h) do { _Pragma("unroll") for (int m = 0; m < 4; ++m) _Pragma("unroll") for (int k = 0; k < 2; ++k) dst[m][k] = *(const PG8_LAS bf16x8*)(lds + PG8_SA(b, h) + aoff + m * 2048 + k * 1024); } while (0)
; #define PG8_LDB(dst, b, h) do { _Pragma("unroll") for (int n = 0; n < 2; ++n) _Pragma("unroll") for (int k = 0; k < 2; ++k) dst[n][k] = *(const PG8_LAS bf16x8*)(lds + PG8_SB(b, h) + boff + n * 2048 + k * 1024); } while (0)
; #define PG8_WAIT_V89() do { if constexpr (SLIVER) PG8_WAIT_V(9); else PG8_WAIT_V(8); } while (0)
; #define PG8_STAGE_S(b, gbase) do { if constexpr (SLIVER) __builtin_amdgcn_global_load_lds((const unsigned*)((const char*)(gbase) + voffS), (PG8_LAS unsigned*)(lds + STAGE_BYTES + (b) * 2048 + wid * 256), 4, 0, 0); } while (0)
; template <class Epi, class Sched, bool ALIGN_EPI = false, bool SP2 = false, bool SLIVER = false>
; __device__ __forceinline__ void gemm_phase(PG8_LAS unsigned char* lds, const Gemm g, const Sched& S, const Epi& E) {
;     ...
;         for (int t = 0; t < nt; t += 2) {
;             const bool last = (t == nt - 2);
;             const char* a1 = cA + (size_t)(t + 1) * kstep;
;             const char* a2 = last ? nA : cA + (size_t)(t + 2) * kstep; const char* b2 = last ? nB : cB + (size_t)(t + 2) * kstep;
;             const char* a3 = a2 + kstep; const char* b3 = b2 + kstep;
;             const char* s1 = cS + (size_t)(t + 1) * kstep; const char* s2 = last ? nS : cS + (size_t)(t + 2) * kstep;
;             if (last && has_next) S.a_ready(nxt);
;             if constexpr (SP2) {
;             PG8_LDB(B0, 0, 0); PG8_LDB(B1, 0, 1); PG8_SCHED; PG8_LDA(At, 0, 0); PG8_STAGE(PG8_SA(1, 1), a1 + hstep, voffA); PG8_STAGE_S(1, s1);
;             PG8_WAIT_V89(); PG8_WAIT_L(0); PG8_BAR; PG8_MMA(0, 0, At, B0); PG8_MMA(0, 1, At, B1); PG8_BAR; PG8_SCHED;
;             PG8_LDA(At, 0, 1); PG8_LDS_S(0); PG8_STAGE(PG8_SB(0, 0), b2, voffB); PG8_STAGE(PG8_SB(0, 1), b2 + hstep, voffB); PG8_STAGE(PG8_SA(0, 0), a2, voffA);
.LBB0_811:
	s_add_u32 s13, s90, s62
	s_addc_u32 s40, s91, s63
	s_add_u32 s13, s13, 0x100
	s_addc_u32 s66, s40, 0
	s_add_u32 s68, s2, s62
	s_addc_u32 s67, s3, s63
	s_add_i32 s69, 0, 0x10000
	s_cmpk_eq_i32 s62, 0x2b00
	s_cselect_b64 s[80:81], -1, 0
	s_and_b64 s[40:41], s[80:81], exec
	s_cselect_b32 s41, s85, s66
	s_cselect_b32 s40, s84, s13
	v_add_u32_e32 v66, s69, v220
	s_cselect_b32 s67, s87, s67
	s_cselect_b32 s66, s86, s68
	s_add_i32 s13, 0, 0x14000
	ds_read_b128 v[154:157], v66
	ds_read_b128 v[158:161], v66 offset:1024
	ds_read_b128 v[162:165], v66 offset:2048
	ds_read_b128 v[174:177], v66 offset:3072
	v_add_u32_e32 v66, s13, v220
	ds_read_b128 v[184:187], v66
	ds_read_b128 v[188:191], v66 offset:1024
	ds_read_b128 v[192:195], v66 offset:2048
	ds_read_b128 v[180:183], v66 offset:3072
	v_lshl_add_u64 v[146:147], v[214:215], 0, s[62:63]
	v_lshl_add_u64 v[148:149], v[146:147], 0, s[8:9]
	s_add_i32 m0, s19, 0xc000
	s_mov_b64 s[94:95], 0x210080
	ds_read_b128 v[66:69], v223
	ds_read_b128 v[70:73], v223 offset:1024
	ds_read_b128 v[74:77], v223 offset:2048
	ds_read_b128 v[78:81], v223 offset:3072
	ds_read_b128 v[216:219], v223 offset:4096
	ds_read_b128 v[224:227], v223 offset:5120
	ds_read_b128 v[228:231], v223 offset:6144
	ds_read_b128 v[232:235], v223 offset:7168
	global_load_lds_dwordx4 v[148:149], off
	v_lshl_add_u64 v[146:147], v[146:147], 0, s[94:95]
	s_add_i32 m0, s19, 0xe000
	s_nop 0
	global_load_lds_dwordx4 v[146:147], off
	v_lshl_add_u64 v[146:147], v[212:213], 0, s[62:63]
	s_add_i32 m0, s96, 0x20800
	s_nop 0
	global_load_lds_dword v[146:147], off
	s_waitcnt vmcnt(9)
	s_waitcnt lgkmcnt(0)
	s_setprio 1
	s_barrier
	v_mfma_f32_16x16x32_bf16 v[146:149], v[154:157], v[66:69], v[170:173]
	v_mfma_f32_16x16x32_bf16 v[150:153], v[162:165], v[66:69], v[166:169]
	v_mfma_f32_16x16x32_bf16 v[134:137], v[154:157], v[74:77], v[134:137]
	v_mfma_f32_16x16x32_bf16 v[130:133], v[162:165], v[74:77], v[130:133]
	v_mfma_f32_16x16x32_bf16 v[118:121], v[154:157], v[216:219], v[118:121]
	v_mfma_f32_16x16x32_bf16 v[114:117], v[162:165], v[216:219], v[114:117]
	v_mfma_f32_16x16x32_bf16 v[102:105], v[154:157], v[228:231], v[102:105]
	v_mfma_f32_16x16x32_bf16 v[98:101], v[162:165], v[228:231], v[98:101]
	v_mfma_f32_16x16x32_bf16 v[146:149], v[158:161], v[70:73], v[146:149]
	v_mfma_f32_16x16x32_bf16 v[150:153], v[174:177], v[70:73], v[150:153]
	v_mfma_f32_16x16x32_bf16 v[134:137], v[158:161], v[78:81], v[134:137]
	v_mfma_f32_16x16x32_bf16 v[130:133], v[174:177], v[78:81], v[130:133]
	v_mfma_f32_16x16x32_bf16 v[118:121], v[158:161], v[224:227], v[118:121]
	v_mfma_f32_16x16x32_bf16 v[114:117], v[174:177], v[224:227], v[114:117]
	v_mfma_f32_16x16x32_bf16 v[102:105], v[158:161], v[232:235], v[102:105]
	v_mfma_f32_16x16x32_bf16 v[98:101], v[174:177], v[232:235], v[98:101]
	s_setprio 0
	s_setprio 1
	v_mfma_f32_16x16x32_bf16 v[142:145], v[184:187], v[66:69], v[142:145]
	v_mfma_f32_16x16x32_bf16 v[66:69], v[192:195], v[66:69], v[138:141]
	v_mfma_f32_16x16x32_bf16 v[138:141], v[180:183], v[70:73], v[66:69]
	v_mfma_f32_16x16x32_bf16 v[66:69], v[184:187], v[74:77], v[126:129]
	v_mfma_f32_16x16x32_bf16 v[126:129], v[188:191], v[78:81], v[66:69]
	v_mfma_f32_16x16x32_bf16 v[66:69], v[192:195], v[74:77], v[122:125]
	v_mfma_f32_16x16x32_bf16 v[122:125], v[180:183], v[78:81], v[66:69]
	v_mfma_f32_16x16x32_bf16 v[66:69], v[184:187], v[216:219], v[110:113]
	v_mfma_f32_16x16x32_bf16 v[110:113], v[188:191], v[224:227], v[66:69]
	v_mfma_f32_16x16x32_bf16 v[66:69], v[192:195], v[216:219], v[106:109]
	v_mfma_f32_16x16x32_bf16 v[106:109], v[180:183], v[224:227], v[66:69]
	v_mfma_f32_16x16x32_bf16 v[66:69], v[184:187], v[228:231], v[94:97]
	v_mfma_f32_16x16x32_bf16 v[94:97], v[188:191], v[232:235], v[66:69]
	v_mfma_f32_16x16x32_bf16 v[66:69], v[192:195], v[228:231], v[90:93]
	v_mfma_f32_16x16x32_bf16 v[142:145], v[188:191], v[70:73], v[142:145]
	v_mfma_f32_16x16x32_bf16 v[90:93], v[180:183], v[232:235], v[66:69]
	s_barrier
	s_setprio 0
	s_add_i32 s68, 0, 0x20000
	v_lshl_add_u64 v[216:217], s[66:67], 0, v[198:199]
	s_add_i32 s66, s69, s18
	v_add_u32_e32 v74, s68, v221
	v_add_u32_e32 v75, s68, v222
	s_mov_b32 m0, s66
	ds_read_b128 v[66:69], v223 offset:16384
	ds_read_b128 v[70:73], v223 offset:17408
	ds_read_b128 v[224:227], v223 offset:18432
	ds_read_b128 v[228:231], v223 offset:19456
	ds_read_b128 v[232:235], v223 offset:20480
	ds_read_b128 v[240:243], v223 offset:21504
	ds_read_b128 v[244:247], v223 offset:22528
	ds_read_b128 v[248:251], v223 offset:23552
	ds_read_b128 v[166:169], v74
	ds_read_b128 v[170:173], v75
	global_load_lds_dwordx4 v[216:217], off
	v_lshl_add_u64 v[74:75], v[216:217], 0, s[64:65]
	s_add_i32 m0, s66, 0x2000
	s_add_i32 s13, s13, s18
	global_load_lds_dwordx4 v[74:75], off
	v_lshl_add_u64 v[74:75], v[216:217], 0, s[0:1]
	s_mov_b32 m0, s13
	v_lshl_add_u64 v[218:219], s[40:41], 0, v[196:197]
	global_load_lds_dwordx4 v[74:75], off
	v_lshl_add_u64 v[74:75], v[216:217], 0, s[74:75]
	s_add_i32 m0, s13, 0x2000
	s_nop 0
	global_load_lds_dwordx4 v[74:75], off
	s_mov_b32 m0, s19
	v_lshl_add_u64 v[74:75], v[218:219], 0, s[64:65]
	global_load_lds_dwordx4 v[218:219], off
	s_mov_b32 m0, s52
	s_nop 0
	global_load_lds_dwordx4 v[74:75], off
	s_waitcnt vmcnt(9)
	s_waitcnt lgkmcnt(0)
	s_setprio 1
	s_barrier
; #define PG8_STAGE(bufoff, gbase, voff) do { _Pragma("unroll") for (int _i = 0; _i < 2; ++_i) \
;         __builtin_amdgcn_global_load_lds((const unsigned*)((const char*)(gbase) + (size_t)_i * qstep + (voff)[0]), (PG8_LAS unsigned*)(lds + (bufoff) + ldsw + _i * 8192), 16, 0, 0); } while (0)
; #define PG8_LDA(dst, b, h) do { _Pragma("unroll") for (int m = 0; m < 4; ++m) _Pragma("unroll") for (int k = 0; k < 2; ++k) dst[m][k] = *(const PG8_LAS bf16x8*)(lds + PG8_SA(b, h) + aoff + m * 2048 + k * 1024); } while (0)
; #define PG8_LDB(dst, b, h) do { _Pragma("unroll") for (int n = 0; n < 2; ++n) _Pragma("unroll") for (int k = 0; k < 2; ++k) dst[n][k] = *(const PG8_LAS bf16x8*)(lds + PG8_SB(b, h) + boff + n * 2048 + k * 1024); } while (0)
; #define PG8_MMA(ai, bj, At, Bt) do { __builtin_amdgcn_s_setprio(1); _Pragma("unroll") for (int m = 0; m < 4; ++m) _Pragma("unroll") for (int n = 0; n < 2; ++n) _Pragma("unroll") for (int k = 0; k < 2; ++k) \
;         acc[ai][bj][m][n] = __builtin_amdgcn_mfma_f32_16x16x32_bf16(Bt[n][k], At[m][k], acc[ai][bj][m][n], 0, 0, 0); __builtin_amdgcn_s_setprio(0); } while (0)
; #define PG8_WAIT_V89() do { if constexpr (SLIVER) PG8_WAIT_V(9); else PG8_WAIT_V(8); } while (0)
; #define PG8_STAGE_S(b, gbase) do { if constexpr (SLIVER) __builtin_amdgcn_global_load_lds((const unsigned*)((const char*)(gbase) + voffS), (PG8_LAS unsigned*)(lds + STAGE_BYTES + (b) * 2048 + wid * 256), 4, 0, 0); } while (0)
; #define PG8_WAIT_L(n) asm volatile("s_waitcnt lgkmcnt(" #n ")" ::: "memory")
; #define PG8_BAR __builtin_amdgcn_s_barrier()
; #define PG8_SCHED __builtin_amdgcn_sched_barrier(0)
; template <class Epi, class Sched, bool ALIGN_EPI = false, bool SP2 = false, bool SLIVER = false>
; __device__ __forceinline__ void gemm_phase(PG8_LAS unsigned char* lds, const Gemm g, const Sched& S, const Epi& E) {
;     ...
;             PG8_WAIT_V89(); PG8_WAIT_L(0); PG8_BAR; PG8_MMA(1, 0, At, B0); PG8_MMA(1, 1, At, B1); PG8_MMA_S(); PG8_BAR; PG8_SCHED;
;             PG8_LDB(B0, 1, 0); PG8_LDB(B1, 1, 1); PG8_SCHED; PG8_LDA(At, 1, 0); PG8_STAGE(PG8_SA(0, 1), a2 + hstep, voffA); PG8_STAGE_S(0, s2);
;             PG8_WAIT_V89(); PG8_WAIT_L(0); PG8_BAR; PG8_MMA(0, 0, At, B0); PG8_MMA(0, 1, At, B1); PG8_BAR; PG8_SCHED;
	v_mfma_f32_16x16x32_bf16 v[74:77], v[154:157], v[66:69], v[86:89]
	v_mfma_f32_16x16x32_bf16 v[78:81], v[162:165], v[66:69], v[82:85]
	v_mfma_f32_16x16x32_bf16 v[54:57], v[154:157], v[224:227], v[54:57]
	v_mfma_f32_16x16x32_bf16 v[50:53], v[162:165], v[224:227], v[50:53]
	v_mfma_f32_16x16x32_bf16 v[38:41], v[154:157], v[232:235], v[38:41]
	v_mfma_f32_16x16x32_bf16 v[34:37], v[162:165], v[232:235], v[34:37]
	v_mfma_f32_16x16x32_bf16 v[22:25], v[154:157], v[244:247], v[22:25]
	v_mfma_f32_16x16x32_bf16 v[18:21], v[162:165], v[244:247], v[18:21]
	v_mfma_f32_16x16x32_bf16 v[74:77], v[158:161], v[70:73], v[74:77]
	v_mfma_f32_16x16x32_bf16 v[78:81], v[174:177], v[70:73], v[78:81]
	v_mfma_f32_16x16x32_bf16 v[54:57], v[158:161], v[228:231], v[54:57]
	v_mfma_f32_16x16x32_bf16 v[50:53], v[174:177], v[228:231], v[50:53]
	v_mfma_f32_16x16x32_bf16 v[38:41], v[158:161], v[240:243], v[38:41]
	v_mfma_f32_16x16x32_bf16 v[34:37], v[174:177], v[240:243], v[34:37]
	v_mfma_f32_16x16x32_bf16 v[22:25], v[158:161], v[248:251], v[22:25]
	v_mfma_f32_16x16x32_bf16 v[18:21], v[174:177], v[248:251], v[18:21]
	s_setprio 0
	s_setprio 1
	v_mfma_f32_16x16x32_bf16 v[62:65], v[184:187], v[66:69], v[62:65]
	v_mfma_f32_16x16x32_bf16 v[58:61], v[192:195], v[66:69], v[58:61]
	v_mfma_f32_16x16x32_bf16 v[46:49], v[184:187], v[224:227], v[46:49]
	v_mfma_f32_16x16x32_bf16 v[42:45], v[192:195], v[224:227], v[42:45]
	v_mfma_f32_16x16x32_bf16 v[30:33], v[184:187], v[232:235], v[30:33]
	v_mfma_f32_16x16x32_bf16 v[26:29], v[192:195], v[232:235], v[26:29]
	v_mfma_f32_16x16x32_bf16 v[14:17], v[184:187], v[244:247], v[14:17]
	v_mfma_f32_16x16x32_bf16 v[10:13], v[192:195], v[244:247], v[10:13]
	v_mfma_f32_16x16x32_bf16 v[62:65], v[188:191], v[70:73], v[62:65]
	v_mfma_f32_16x16x32_bf16 v[58:61], v[180:183], v[70:73], v[58:61]
	v_mfma_f32_16x16x32_bf16 v[46:49], v[188:191], v[228:231], v[46:49]
	v_mfma_f32_16x16x32_bf16 v[42:45], v[180:183], v[228:231], v[42:45]
	v_mfma_f32_16x16x32_bf16 v[30:33], v[188:191], v[240:243], v[30:33]
	v_mfma_f32_16x16x32_bf16 v[26:29], v[180:183], v[240:243], v[26:29]
	v_mfma_f32_16x16x32_bf16 v[14:17], v[188:191], v[248:251], v[14:17]
	v_mfma_f32_16x16x32_bf16 v[10:13], v[180:183], v[248:251], v[10:13]
	s_setprio 0
	s_setprio 1
	s_and_b64 vcc, exec, s[82:83]
	s_cbranch_vccz .Lslv_b2
	v_mfma_f32_16x16x32_bf16 v[66:69], v[184:187], v[166:169], v[6:9]
	v_mfma_f32_16x16x32_bf16 v[70:73], v[192:195], v[166:169], v[2:5]
	v_mfma_f32_16x16x32_bf16 v[66:69], v[188:191], v[170:173], v[66:69]
	v_mfma_f32_16x16x32_bf16 v[70:73], v[180:183], v[170:173], v[70:73]
	s_branch .LBB0_815
.LBB0_813:
.Lslv_b2:
	v_mfma_f32_16x16x32_bf16 v[6:9], v[154:157], v[166:169], v[6:9]
	v_mfma_f32_16x16x32_bf16 v[2:5], v[162:165], v[166:169], v[2:5]
	v_mfma_f32_16x16x32_bf16 v[66:69], v[158:161], v[170:173], v[6:9]
	v_mfma_f32_16x16x32_bf16 v[70:73], v[174:177], v[170:173], v[2:5]
.LBB0_815:
	s_barrier
	s_setprio 0
	s_add_u32 s13, s92, s62
	s_addc_u32 s66, s93, s63
	s_add_u32 s13, s13, 0x100
	s_addc_u32 s68, s66, 0
	s_and_b64 s[66:67], s[80:81], exec
	s_cselect_b32 s67, s89, s68
	s_cselect_b32 s66, s88, s13
	s_add_i32 s13, 0, 0x18000
	v_add_u32_e32 v2, s13, v220
	s_add_i32 s68, 0, 0x1c000
	ds_read_b128 v[154:157], v2
	ds_read_b128 v[158:161], v2 offset:1024
	ds_read_b128 v[162:165], v2 offset:2048
	ds_read_b128 v[174:177], v2 offset:3072
	v_add_u32_e32 v2, s68, v220
	ds_read_b128 v[184:187], v2
	ds_read_b128 v[188:191], v2 offset:1024
	ds_read_b128 v[192:195], v2 offset:2048
	ds_read_b128 v[180:183], v2 offset:3072
	s_mov_b32 m0, s53
	v_lshl_add_u64 v[166:167], v[218:219], 0, s[0:1]
	ds_read_b128 v[2:5], v223 offset:32768
	ds_read_b128 v[6:9], v223 offset:33792
	ds_read_b128 v[82:85], v223 offset:34816
	ds_read_b128 v[86:89], v223 offset:35840
	ds_read_b128 v[224:227], v223 offset:36864
	ds_read_b128 v[228:231], v223 offset:37888
	ds_read_b128 v[232:235], v223 offset:38912
	ds_read_b128 v[240:243], v223 offset:39936
	global_load_lds_dwordx4 v[166:167], off
	v_lshl_add_u64 v[166:167], v[218:219], 0, s[74:75]
	s_mov_b32 m0, s54
	s_nop 0
	global_load_lds_dwordx4 v[166:167], off
	v_lshl_add_u64 v[166:167], s[66:67], 0, v[200:201]
	s_mov_b32 m0, s55
	s_nop 0
	global_load_lds_dword v[166:167], off
	s_waitcnt vmcnt(9)
	s_waitcnt lgkmcnt(0)
	s_setprio 1
	s_barrier
; #define PG8_SB(B) __builtin_amdgcn_rcpf(1.f + expneg(B))
; #define PG8_SB(B) __builtin_amdgcn_rcpf(1.f + expneg(B))
; #define PG8_STAGE(bufoff, gbase, voff) do { _Pragma("unroll") for (int _i = 0; _i < 2; ++_i) \
;         __builtin_amdgcn_global_load_lds((const unsigned*)((const char*)(gbase) + (size_t)_i * qstep + (voff)[0]), (PG8_LAS unsigned*)(lds + (bufoff) + ldsw + _i * 8192), 16, 0, 0); } while (0)
; #define PG8_LDA(dst, b, h) do { _Pragma("unroll") for (int m = 0; m < 4; ++m) _Pragma("unroll") for (int k = 0; k < 2; ++k) dst[m][k] = *(const PG8_LAS bf16x8*)(lds + PG8_SA(b, h) + aoff + m * 2048 + k * 1024); } while (0)
; #define PG8_LDB(dst, b, h) do { _Pragma("unroll") for (int n = 0; n < 2; ++n) _Pragma("unroll") for (int k = 0; k < 2; ++k) dst[n][k] = *(const PG8_LAS bf16x8*)(lds + PG8_SB(b, h) + boff + n * 2048 + k * 1024); } while (0)
; #define PG8_MMA(ai, bj, At, Bt) do { __builtin_amdgcn_s_setprio(1); _Pragma("unroll") for (int m = 0; m < 4; ++m) _Pragma("unroll") for (int n = 0; n < 2; ++n) _Pragma("unroll") for (int k = 0; k < 2; ++k) \
;         acc[ai][bj][m][n] = __builtin_amdgcn_mfma_f32_16x16x32_bf16(Bt[n][k], At[m][k], acc[ai][bj][m][n], 0, 0, 0); __builtin_amdgcn_s_setprio(0); } while (0)
; #define PG8_WAIT_V89() do { if constexpr (SLIVER) PG8_WAIT_V(9); else PG8_WAIT_V(8); } while (0)
; #define PG8_STAGE_S(b, gbase) do { if constexpr (SLIVER) __builtin_amdgcn_global_load_lds((const unsigned*)((const char*)(gbase) + voffS), (PG8_LAS unsigned*)(lds + STAGE_BYTES + (b) * 2048 + wid * 256), 4, 0, 0); } while (0)
; #define PG8_BAR __builtin_amdgcn_s_barrier()
; template <class Epi, class Sched, bool ALIGN_EPI = false, bool SP2 = false, bool SLIVER = false>
; __device__ __forceinline__ void gemm_phase(PG8_LAS unsigned char* lds, const Gemm g, const Sched& S, const Epi& E) {
;     ...
;             PG8_LDB(B0, 1, 0); PG8_LDB(B1, 1, 1); PG8_SCHED; PG8_LDA(At, 1, 0); PG8_STAGE(PG8_SA(0, 1), a2 + hstep, voffA); PG8_STAGE_S(0, s2);
;             PG8_WAIT_V89(); PG8_WAIT_L(0); PG8_BAR; PG8_MMA(0, 0, At, B0); PG8_MMA(0, 1, At, B1); PG8_BAR; PG8_SCHED;
;             PG8_LDA(At, 1, 1); PG8_LDS_S(1); PG8_STAGE(PG8_SB(1, 0), b3, voffB); PG8_STAGE(PG8_SB(1, 1), b3 + hstep, voffB); PG8_STAGE(PG8_SA(1, 0), a3, voffA);
;             PG8_WAIT_V89(); PG8_WAIT_L(0); PG8_BAR; PG8_MMA(1, 0, At, B0); PG8_MMA(1, 1, At, B1); PG8_MMA_S(); PG8_BAR; PG8_SCHED;
	v_mfma_f32_16x16x32_bf16 v[146:149], v[154:157], v[2:5], v[146:149]
	v_mfma_f32_16x16x32_bf16 v[170:173], v[158:161], v[6:9], v[146:149]
	v_mfma_f32_16x16x32_bf16 v[146:149], v[162:165], v[2:5], v[150:153]
	v_mfma_f32_16x16x32_bf16 v[134:137], v[154:157], v[82:85], v[134:137]
	v_mfma_f32_16x16x32_bf16 v[130:133], v[162:165], v[82:85], v[130:133]
	v_mfma_f32_16x16x32_bf16 v[118:121], v[154:157], v[224:227], v[118:121]
	v_mfma_f32_16x16x32_bf16 v[114:117], v[162:165], v[224:227], v[114:117]
	v_mfma_f32_16x16x32_bf16 v[102:105], v[154:157], v[232:235], v[102:105]
	v_mfma_f32_16x16x32_bf16 v[98:101], v[162:165], v[232:235], v[98:101]
	v_mfma_f32_16x16x32_bf16 v[166:169], v[174:177], v[6:9], v[146:149]
	v_mfma_f32_16x16x32_bf16 v[134:137], v[158:161], v[86:89], v[134:137]
	v_mfma_f32_16x16x32_bf16 v[130:133], v[174:177], v[86:89], v[130:133]
	v_mfma_f32_16x16x32_bf16 v[118:121], v[158:161], v[228:231], v[118:121]
	v_mfma_f32_16x16x32_bf16 v[114:117], v[174:177], v[228:231], v[114:117]
	v_mfma_f32_16x16x32_bf16 v[102:105], v[158:161], v[240:243], v[102:105]
	v_mfma_f32_16x16x32_bf16 v[98:101], v[174:177], v[240:243], v[98:101]
	s_setprio 0
	s_setprio 1
	v_mfma_f32_16x16x32_bf16 v[142:145], v[184:187], v[2:5], v[142:145]
	v_mfma_f32_16x16x32_bf16 v[2:5], v[192:195], v[2:5], v[138:141]
	v_mfma_f32_16x16x32_bf16 v[138:141], v[180:183], v[6:9], v[2:5]
	v_mfma_f32_16x16x32_bf16 v[2:5], v[184:187], v[82:85], v[126:129]
	v_mfma_f32_16x16x32_bf16 v[126:129], v[188:191], v[86:89], v[2:5]
	v_mfma_f32_16x16x32_bf16 v[2:5], v[192:195], v[82:85], v[122:125]
	v_mfma_f32_16x16x32_bf16 v[122:125], v[180:183], v[86:89], v[2:5]
	v_mfma_f32_16x16x32_bf16 v[2:5], v[184:187], v[224:227], v[110:113]
	v_mfma_f32_16x16x32_bf16 v[110:113], v[188:191], v[228:231], v[2:5]
	v_mfma_f32_16x16x32_bf16 v[2:5], v[192:195], v[224:227], v[106:109]
	v_mfma_f32_16x16x32_bf16 v[106:109], v[180:183], v[228:231], v[2:5]
	v_mfma_f32_16x16x32_bf16 v[2:5], v[184:187], v[232:235], v[94:97]
	v_mfma_f32_16x16x32_bf16 v[94:97], v[188:191], v[240:243], v[2:5]
	v_mfma_f32_16x16x32_bf16 v[2:5], v[192:195], v[232:235], v[90:93]
	v_mfma_f32_16x16x32_bf16 v[142:145], v[188:191], v[6:9], v[142:145]
	v_mfma_f32_16x16x32_bf16 v[90:93], v[180:183], v[240:243], v[2:5]
	s_barrier
	s_setprio 0
	s_add_i32 s66, 0, 0x20800
	v_add_u32_e32 v82, s66, v221
	v_add_u32_e32 v83, s66, v222
	s_add_i32 s13, s13, s18
	ds_read_b128 v[2:5], v223 offset:49152
	ds_read_b128 v[6:9], v223 offset:50176
	ds_read_b128 v[224:227], v223 offset:51200
	ds_read_b128 v[228:231], v223 offset:52224
	ds_read_b128 v[232:235], v223 offset:53248
	ds_read_b128 v[240:243], v223 offset:54272
	ds_read_b128 v[244:247], v223 offset:55296
	ds_read_b128 v[248:251], v223 offset:56320
	ds_read_b128 v[146:149], v82
	ds_read_b128 v[150:153], v83
	v_lshl_add_u64 v[82:83], v[216:217], 0, s[26:27]
	s_mov_b32 m0, s13
	s_mov_b64 s[66:67], 0x210080
	global_load_lds_dwordx4 v[82:83], off
	v_lshl_add_u64 v[82:83], v[216:217], 0, s[60:61]
	s_add_i32 m0, s13, 0x2000
	s_add_i32 s13, s68, s18
	global_load_lds_dwordx4 v[82:83], off
	v_lshl_add_u64 v[82:83], v[216:217], 0, s[8:9]
	s_mov_b32 m0, s13
	s_nop 0
	global_load_lds_dwordx4 v[82:83], off
	v_lshl_add_u64 v[82:83], v[216:217], 0, s[66:67]
	s_add_i32 m0, s13, 0x2000
	s_nop 0
	global_load_lds_dwordx4 v[82:83], off
	v_lshl_add_u64 v[82:83], v[218:219], 0, s[26:27]
	s_mov_b32 m0, s10
	s_nop 0
	global_load_lds_dwordx4 v[82:83], off
	v_lshl_add_u64 v[82:83], v[218:219], 0, s[60:61]
	s_mov_b32 m0, s48
	s_nop 0
	global_load_lds_dwordx4 v[82:83], off
	s_waitcnt vmcnt(9)
	s_waitcnt lgkmcnt(0)
	s_setprio 1
	s_barrier
	v_mfma_f32_16x16x32_bf16 v[74:77], v[154:157], v[2:5], v[74:77]
	v_mfma_f32_16x16x32_bf16 v[86:89], v[158:161], v[6:9], v[74:77]
	v_mfma_f32_16x16x32_bf16 v[74:77], v[162:165], v[2:5], v[78:81]
	v_mfma_f32_16x16x32_bf16 v[54:57], v[154:157], v[224:227], v[54:57]
	v_mfma_f32_16x16x32_bf16 v[50:53], v[162:165], v[224:227], v[50:53]
	v_mfma_f32_16x16x32_bf16 v[38:41], v[154:157], v[232:235], v[38:41]
	v_mfma_f32_16x16x32_bf16 v[34:37], v[162:165], v[232:235], v[34:37]
	v_mfma_f32_16x16x32_bf16 v[22:25], v[154:157], v[244:247], v[22:25]
	v_mfma_f32_16x16x32_bf16 v[18:21], v[162:165], v[244:247], v[18:21]
	v_mfma_f32_16x16x32_bf16 v[82:85], v[174:177], v[6:9], v[74:77]
	v_mfma_f32_16x16x32_bf16 v[54:57], v[158:161], v[228:231], v[54:57]
	v_mfma_f32_16x16x32_bf16 v[50:53], v[174:177], v[228:231], v[50:53]
	v_mfma_f32_16x16x32_bf16 v[38:41], v[158:161], v[240:243], v[38:41]
	v_mfma_f32_16x16x32_bf16 v[34:37], v[174:177], v[240:243], v[34:37]
	v_mfma_f32_16x16x32_bf16 v[22:25], v[158:161], v[248:251], v[22:25]
	v_mfma_f32_16x16x32_bf16 v[18:21], v[174:177], v[248:251], v[18:21]
	s_setprio 0
	s_setprio 1
	v_mfma_f32_16x16x32_bf16 v[62:65], v[184:187], v[2:5], v[62:65]
	v_mfma_f32_16x16x32_bf16 v[2:5], v[192:195], v[2:5], v[58:61]
	v_mfma_f32_16x16x32_bf16 v[58:61], v[180:183], v[6:9], v[2:5]
	v_mfma_f32_16x16x32_bf16 v[2:5], v[184:187], v[224:227], v[46:49]
	v_mfma_f32_16x16x32_bf16 v[46:49], v[188:191], v[228:231], v[2:5]
	v_mfma_f32_16x16x32_bf16 v[2:5], v[192:195], v[224:227], v[42:45]
	v_mfma_f32_16x16x32_bf16 v[42:45], v[180:183], v[228:231], v[2:5]
	v_mfma_f32_16x16x32_bf16 v[2:5], v[184:187], v[232:235], v[30:33]
	v_mfma_f32_16x16x32_bf16 v[30:33], v[188:191], v[240:243], v[2:5]
	v_mfma_f32_16x16x32_bf16 v[2:5], v[192:195], v[232:235], v[26:29]
	v_mfma_f32_16x16x32_bf16 v[26:29], v[180:183], v[240:243], v[2:5]
	v_mfma_f32_16x16x32_bf16 v[2:5], v[184:187], v[244:247], v[14:17]
	v_mfma_f32_16x16x32_bf16 v[14:17], v[188:191], v[248:251], v[2:5]
	v_mfma_f32_16x16x32_bf16 v[2:5], v[192:195], v[244:247], v[10:13]
	v_mfma_f32_16x16x32_bf16 v[62:65], v[188:191], v[6:9], v[62:65]
	v_mfma_f32_16x16x32_bf16 v[10:13], v[180:183], v[248:251], v[2:5]
	s_setprio 0
	s_setprio 1
	s_and_b64 vcc, exec, s[82:83]
	s_cbranch_vccz .Lslv_c2
	v_mfma_f32_16x16x32_bf16 v[2:5], v[184:187], v[146:149], v[66:69]
	v_mfma_f32_16x16x32_bf16 v[6:9], v[188:191], v[150:153], v[2:5]
	v_mfma_f32_16x16x32_bf16 v[2:5], v[192:195], v[146:149], v[70:73]
	v_mfma_f32_16x16x32_bf16 v[2:5], v[180:183], v[150:153], v[2:5]
	s_branch .LBB0_810
.LBB0_817:
.Lslv_c2:
	v_mfma_f32_16x16x32_bf16 v[2:5], v[154:157], v[146:149], v[66:69]
	v_mfma_f32_16x16x32_bf16 v[6:9], v[158:161], v[150:153], v[2:5]
	v_mfma_f32_16x16x32_bf16 v[2:5], v[162:165], v[146:149], v[70:73]
	v_mfma_f32_16x16x32_bf16 v[2:5], v[174:177], v[150:153], v[2:5]
	s_branch .LBB0_810

; #define PG8_STAGE(bufoff, gbase, voff) do { _Pragma("unroll") for (int _i = 0; _i < 2; ++_i) \
;         __builtin_amdgcn_global_load_lds((const unsigned*)((const char*)(gbase) + (size_t)_i * qstep + (voff)[0]), (PG8_LAS unsigned*)(lds + (bufoff) + ldsw + _i * 8192), 16, 0, 0); } while (0)
; #define PG8_LDA(dst, b, h) do { _Pragma("unroll") for (int m = 0; m < 4; ++m) _Pragma("unroll") for (int k = 0; k < 2; ++k) dst[m][k] = *(const PG8_LAS bf16x8*)(lds + PG8_SA(b, h) + aoff + m * 2048 + k * 1024); } while (0)
; #define PG8_LDB(dst, b, h) do { _Pragma("unroll") for (int n = 0; n < 2; ++n) _Pragma("unroll") for (int k = 0; k < 2; ++k) dst[n][k] = *(const PG8_LAS bf16x8*)(lds + PG8_SB(b, h) + boff + n * 2048 + k * 1024); } while (0)
; #define PG8_MMA(ai, bj, At, Bt) do { __builtin_amdgcn_s_setprio(1); _Pragma("unroll") for (int m = 0; m < 4; ++m) _Pragma("unroll") for (int n = 0; n < 2; ++n) _Pragma("unroll") for (int k = 0; k < 2; ++k) \
;         acc[ai][bj][m][n] = __builtin_amdgcn_mfma_f32_16x16x32_bf16(Bt[n][k], At[m][k], acc[ai][bj][m][n], 0, 0, 0); __builtin_amdgcn_s_setprio(0); } while (0)
; #define PG8_WAIT_V89() do { if constexpr (SLIVER) PG8_WAIT_V(9); else PG8_WAIT_V(8); } while (0)
; #define PG8_WAIT_L(n) asm volatile("s_waitcnt lgkmcnt(" #n ")" ::: "memory")
; #define PG8_BAR __builtin_amdgcn_s_barrier()
; template <class Epi, class Sched, bool ALIGN_EPI = false, bool SP2 = false, bool SLIVER = false>
; __device__ __forceinline__ void gemm_phase(PG8_LAS unsigned char* lds, const Gemm g, const Sched& S, const Epi& E) {
;     ...
;         for (int t = 0; t < nt; t += 2) {
;             const bool last = (t == nt - 2);
;             const char* a1 = cA + (size_t)(t + 1) * kstep;
;             const char* a2 = last ? nA : cA + (size_t)(t + 2) * kstep; const char* b2 = last ? nB : cB + (size_t)(t + 2) * kstep;
;             const char* a3 = a2 + kstep; const char* b3 = b2 + kstep;
;             const char* s1 = cS + (size_t)(t + 1) * kstep; const char* s2 = last ? nS : cS + (size_t)(t + 2) * kstep;
;             if (last && has_next) S.a_ready(nxt);
;             if constexpr (SP2) {
;             PG8_LDB(B0, 0, 0); PG8_LDB(B1, 0, 1); PG8_SCHED; PG8_LDA(At, 0, 0); PG8_STAGE(PG8_SA(1, 1), a1 + hstep, voffA); PG8_STAGE_S(1, s1);
;             PG8_WAIT_V89(); PG8_WAIT_L(0); PG8_BAR; PG8_MMA(0, 0, At, B0); PG8_MMA(0, 1, At, B1); PG8_BAR; PG8_SCHED;
.LBB0_934:
	s_cmp_eq_u32 s66, s62
	s_cselect_b64 s[80:81], -1, 0
	s_add_u32 s12, s42, s62
	s_addc_u32 s13, s43, s63
	s_add_u32 s40, s12, 0x100
	s_addc_u32 s41, s13, 0
	s_and_b64 s[12:13], s[80:81], exec
	s_cselect_b32 s41, s95, s41
	s_cselect_b32 s40, s94, s40
	s_add_u32 s68, s17, s62
	s_addc_u32 s69, s45, s63
	s_add_i32 s76, 0, 0x10000
	s_and_b64 s[12:13], s[80:81], exec
	v_add_u32_e32 v138, s76, v212
	s_cselect_b32 s13, s97, s69
	s_cselect_b32 s12, s96, s68
	s_add_i32 s68, 0, 0x14000
	ds_read_b128 v[146:149], v138
	ds_read_b128 v[150:153], v138 offset:1024
	ds_read_b128 v[154:157], v138 offset:2048
	ds_read_b128 v[158:161], v138 offset:3072
	v_add_u32_e32 v138, s68, v212
	ds_read_b128 v[166:169], v138
	ds_read_b128 v[170:173], v138 offset:1024
	ds_read_b128 v[174:177], v138 offset:2048
	ds_read_b128 v[162:165], v138 offset:3072
	v_lshl_add_u64 v[202:203], v[198:199], 0, s[62:63]
	s_mov_b64 vcc, 0x90080
	v_lshl_add_u64 v[208:209], v[202:203], 0, vcc
	s_add_i32 m0, s93, 0xc000
	s_mov_b64 vcc, 0xd8080
	ds_read_b128 v[138:141], v215
	ds_read_b128 v[142:145], v215 offset:1024
	ds_read_b128 v[180:183], v215 offset:2048
	ds_read_b128 v[184:187], v215 offset:3072
	ds_read_b128 v[216:219], v215 offset:4096
	ds_read_b128 v[220:223], v215 offset:5120
	ds_read_b128 v[224:227], v215 offset:6144
	ds_read_b128 v[228:231], v215 offset:7168
	global_load_lds_dwordx4 v[208:209], off
	v_lshl_add_u64 v[202:203], v[202:203], 0, vcc
	s_add_i32 m0, s93, 0xe000
	s_nop 0
	global_load_lds_dwordx4 v[202:203], off
	v_lshl_add_u64 v[202:203], v[200:201], 0, s[62:63]
	s_add_i32 m0, s50, 0x20800
	s_nop 0
	global_load_lds_dword v[202:203], off
	s_waitcnt vmcnt(9)
	s_waitcnt lgkmcnt(0)
	s_setprio 1
	s_barrier
	v_mfma_f32_16x16x32_bf16 v[134:137], v[146:149], v[138:141], v[134:137]
	v_mfma_f32_16x16x32_bf16 v[130:133], v[154:157], v[138:141], v[130:133]
	v_mfma_f32_16x16x32_bf16 v[126:129], v[146:149], v[180:183], v[126:129]
	v_mfma_f32_16x16x32_bf16 v[122:125], v[154:157], v[180:183], v[122:125]
	v_mfma_f32_16x16x32_bf16 v[114:117], v[146:149], v[216:219], v[114:117]
	v_mfma_f32_16x16x32_bf16 v[106:109], v[154:157], v[216:219], v[106:109]
	v_mfma_f32_16x16x32_bf16 v[98:101], v[146:149], v[224:227], v[98:101]
	v_mfma_f32_16x16x32_bf16 v[90:93], v[154:157], v[224:227], v[90:93]
	v_mfma_f32_16x16x32_bf16 v[134:137], v[150:153], v[142:145], v[134:137]
	v_mfma_f32_16x16x32_bf16 v[130:133], v[158:161], v[142:145], v[130:133]
	v_mfma_f32_16x16x32_bf16 v[126:129], v[150:153], v[184:187], v[126:129]
	v_mfma_f32_16x16x32_bf16 v[122:125], v[158:161], v[184:187], v[122:125]
	v_mfma_f32_16x16x32_bf16 v[114:117], v[150:153], v[220:223], v[114:117]
	v_mfma_f32_16x16x32_bf16 v[106:109], v[158:161], v[220:223], v[106:109]
	v_mfma_f32_16x16x32_bf16 v[98:101], v[150:153], v[228:231], v[98:101]
	v_mfma_f32_16x16x32_bf16 v[90:93], v[158:161], v[228:231], v[90:93]
	s_setprio 0
	s_setprio 1
	v_mfma_f32_16x16x32_bf16 v[118:121], v[166:169], v[138:141], v[118:121]
	v_mfma_f32_16x16x32_bf16 v[110:113], v[174:177], v[138:141], v[110:113]
	v_mfma_f32_16x16x32_bf16 v[102:105], v[166:169], v[180:183], v[102:105]
	v_mfma_f32_16x16x32_bf16 v[94:97], v[174:177], v[180:183], v[94:97]
	v_mfma_f32_16x16x32_bf16 v[86:89], v[166:169], v[216:219], v[86:89]
	v_mfma_f32_16x16x32_bf16 v[82:85], v[174:177], v[216:219], v[82:85]
	v_mfma_f32_16x16x32_bf16 v[78:81], v[166:169], v[224:227], v[78:81]
	v_mfma_f32_16x16x32_bf16 v[74:77], v[174:177], v[224:227], v[74:77]
	v_mfma_f32_16x16x32_bf16 v[118:121], v[170:173], v[142:145], v[118:121]
	v_mfma_f32_16x16x32_bf16 v[110:113], v[162:165], v[142:145], v[110:113]
	v_mfma_f32_16x16x32_bf16 v[102:105], v[170:173], v[184:187], v[102:105]
	v_mfma_f32_16x16x32_bf16 v[94:97], v[162:165], v[184:187], v[94:97]
	v_mfma_f32_16x16x32_bf16 v[86:89], v[170:173], v[220:223], v[86:89]
	v_mfma_f32_16x16x32_bf16 v[82:85], v[162:165], v[220:223], v[82:85]
	v_mfma_f32_16x16x32_bf16 v[78:81], v[170:173], v[228:231], v[78:81]
	v_mfma_f32_16x16x32_bf16 v[74:77], v[162:165], v[228:231], v[74:77]
	s_barrier
; #define PG8_SB(B) __builtin_amdgcn_rcpf(1.f + expneg(B))
; #define PG8_SB(B) __builtin_amdgcn_rcpf(1.f + expneg(B))
; #define PG8_STAGE(bufoff, gbase, voff) do { _Pragma("unroll") for (int _i = 0; _i < 2; ++_i) \
;         __builtin_amdgcn_global_load_lds((const unsigned*)((const char*)(gbase) + (size_t)_i * qstep + (voff)[0]), (PG8_LAS unsigned*)(lds + (bufoff) + ldsw + _i * 8192), 16, 0, 0); } while (0)
; #define PG8_LDA(dst, b, h) do { _Pragma("unroll") for (int m = 0; m < 4; ++m) _Pragma("unroll") for (int k = 0; k < 2; ++k) dst[m][k] = *(const PG8_LAS bf16x8*)(lds + PG8_SA(b, h) + aoff + m * 2048 + k * 1024); } while (0)
; #define PG8_MMA(ai, bj, At, Bt) do { __builtin_amdgcn_s_setprio(1); _Pragma("unroll") for (int m = 0; m < 4; ++m) _Pragma("unroll") for (int n = 0; n < 2; ++n) _Pragma("unroll") for (int k = 0; k < 2; ++k) \
;         acc[ai][bj][m][n] = __builtin_amdgcn_mfma_f32_16x16x32_bf16(Bt[n][k], At[m][k], acc[ai][bj][m][n], 0, 0, 0); __builtin_amdgcn_s_setprio(0); } while (0)
; #define PG8_WAIT_V89() do { if constexpr (SLIVER) PG8_WAIT_V(9); else PG8_WAIT_V(8); } while (0)
; #define PG8_LDS_S(b) do { if constexpr (SLIVER) { Sf[0] = *(const PG8_LAS bf16x8*)(lds + STAGE_BYTES + (b) * 2048 + soff0); Sf[1] = *(const PG8_LAS bf16x8*)(lds + STAGE_BYTES + (b) * 2048 + (soff0 ^ 64)); } } while (0)
; #define PG8_WAIT_L(n) asm volatile("s_waitcnt lgkmcnt(" #n ")" ::: "memory")
; #define PG8_BAR __builtin_amdgcn_s_barrier()
; #define PG8_SCHED __builtin_amdgcn_sched_barrier(0)
; template <class Epi, class Sched, bool ALIGN_EPI = false, bool SP2 = false, bool SLIVER = false>
; __device__ __forceinline__ void gemm_phase(PG8_LAS unsigned char* lds, const Gemm g, const Sched& S, const Epi& E) {
;     ...
;             PG8_LDA(At, 0, 1); PG8_LDS_S(0); PG8_STAGE(PG8_SB(0, 0), b2, voffB); PG8_STAGE(PG8_SB(0, 1), b2 + hstep, voffB); PG8_STAGE(PG8_SA(0, 0), a2, voffA);
;             PG8_WAIT_V89(); PG8_WAIT_L(0); PG8_BAR; PG8_MMA(1, 0, At, B0); PG8_MMA(1, 1, At, B1); PG8_MMA_S(); PG8_BAR; PG8_SCHED;
	s_setprio 0
	s_add_i32 s69, 0, 0x20000
	v_lshl_add_u64 v[202:203], s[12:13], 0, v[190:191]
	s_add_i32 s12, s76, s92
	v_add_u32_e32 v178, s69, v213
	v_add_u32_e32 v184, s69, v214
	s_mov_b32 m0, s12
	ds_read_b128 v[138:141], v215 offset:16384
	ds_read_b128 v[142:145], v215 offset:17408
	ds_read_b128 v[216:219], v215 offset:18432
	ds_read_b128 v[220:223], v215 offset:19456
	ds_read_b128 v[224:227], v215 offset:20480
	ds_read_b128 v[228:231], v215 offset:21504
	ds_read_b128 v[232:235], v215 offset:22528
	ds_read_b128 v[240:243], v215 offset:23552
	ds_read_b128 v[180:183], v178
	ds_read_b128 v[184:187], v184
	global_load_lds_dwordx4 v[202:203], off
	v_lshl_add_u64 v[208:209], v[202:203], 0, s[70:71]
	s_add_i32 m0, s12, 0x2000
	s_add_i32 s12, s68, s92
	global_load_lds_dwordx4 v[208:209], off
	v_lshl_add_u64 v[208:209], v[202:203], 0, s[46:47]
	s_mov_b32 m0, s12
	v_lshl_add_u64 v[210:211], s[40:41], 0, v[188:189]
	global_load_lds_dwordx4 v[208:209], off
	v_lshl_add_u64 v[208:209], v[202:203], 0, s[6:7]
	s_add_i32 m0, s12, 0x2000
	s_nop 0
	global_load_lds_dwordx4 v[208:209], off
	s_mov_b32 m0, s93
	v_lshl_add_u64 v[208:209], v[210:211], 0, s[70:71]
	global_load_lds_dwordx4 v[210:211], off
	s_mov_b32 m0, s48
	s_nop 0
	global_load_lds_dwordx4 v[208:209], off
	s_waitcnt vmcnt(9)
	s_waitcnt lgkmcnt(0)
	s_setprio 1
	s_barrier
	v_mfma_f32_16x16x32_bf16 v[70:73], v[146:149], v[138:141], v[70:73]
	v_mfma_f32_16x16x32_bf16 v[66:69], v[154:157], v[138:141], v[66:69]
	v_mfma_f32_16x16x32_bf16 v[62:65], v[146:149], v[216:219], v[62:65]
	v_mfma_f32_16x16x32_bf16 v[58:61], v[154:157], v[216:219], v[58:61]
	v_mfma_f32_16x16x32_bf16 v[50:53], v[146:149], v[224:227], v[50:53]
	v_mfma_f32_16x16x32_bf16 v[42:45], v[154:157], v[224:227], v[42:45]
	v_mfma_f32_16x16x32_bf16 v[34:37], v[146:149], v[232:235], v[34:37]
	v_mfma_f32_16x16x32_bf16 v[26:29], v[154:157], v[232:235], v[26:29]
	v_mfma_f32_16x16x32_bf16 v[70:73], v[150:153], v[142:145], v[70:73]
	v_mfma_f32_16x16x32_bf16 v[66:69], v[158:161], v[142:145], v[66:69]
	v_mfma_f32_16x16x32_bf16 v[62:65], v[150:153], v[220:223], v[62:65]
	v_mfma_f32_16x16x32_bf16 v[58:61], v[158:161], v[220:223], v[58:61]
	v_mfma_f32_16x16x32_bf16 v[50:53], v[150:153], v[228:231], v[50:53]
	v_mfma_f32_16x16x32_bf16 v[42:45], v[158:161], v[228:231], v[42:45]
	v_mfma_f32_16x16x32_bf16 v[34:37], v[150:153], v[240:243], v[34:37]
	v_mfma_f32_16x16x32_bf16 v[26:29], v[158:161], v[240:243], v[26:29]
	s_setprio 0
	s_setprio 1
	v_mfma_f32_16x16x32_bf16 v[54:57], v[166:169], v[138:141], v[54:57]
	v_mfma_f32_16x16x32_bf16 v[46:49], v[174:177], v[138:141], v[46:49]
	v_mfma_f32_16x16x32_bf16 v[38:41], v[166:169], v[216:219], v[38:41]
	v_mfma_f32_16x16x32_bf16 v[30:33], v[174:177], v[216:219], v[30:33]
	v_mfma_f32_16x16x32_bf16 v[22:25], v[166:169], v[224:227], v[22:25]
	v_mfma_f32_16x16x32_bf16 v[18:21], v[174:177], v[224:227], v[18:21]
	v_mfma_f32_16x16x32_bf16 v[14:17], v[166:169], v[232:235], v[14:17]
	v_mfma_f32_16x16x32_bf16 v[10:13], v[174:177], v[232:235], v[10:13]
	v_mfma_f32_16x16x32_bf16 v[54:57], v[170:173], v[142:145], v[54:57]
	v_mfma_f32_16x16x32_bf16 v[46:49], v[162:165], v[142:145], v[46:49]
	v_mfma_f32_16x16x32_bf16 v[38:41], v[170:173], v[220:223], v[38:41]
	v_mfma_f32_16x16x32_bf16 v[30:33], v[162:165], v[220:223], v[30:33]
	v_mfma_f32_16x16x32_bf16 v[22:25], v[170:173], v[228:231], v[22:25]
	v_mfma_f32_16x16x32_bf16 v[18:21], v[162:165], v[228:231], v[18:21]
	v_mfma_f32_16x16x32_bf16 v[14:17], v[170:173], v[240:243], v[14:17]
	v_mfma_f32_16x16x32_bf16 v[10:13], v[162:165], v[240:243], v[10:13]
	s_setprio 0
	s_setprio 1
	s_and_b64 vcc, exec, s[90:91]
	s_cbranch_vccz .Lslv_b3
	v_mfma_f32_16x16x32_bf16 v[138:141], v[166:169], v[180:183], v[6:9]
	v_mfma_f32_16x16x32_bf16 v[142:145], v[174:177], v[180:183], v[2:5]
	v_mfma_f32_16x16x32_bf16 v[138:141], v[170:173], v[184:187], v[138:141]
	v_mfma_f32_16x16x32_bf16 v[142:145], v[162:165], v[184:187], v[142:145]
	s_branch .LBB0_938

; #define PG8_STAGE(bufoff, gbase, voff) do { _Pragma("unroll") for (int _i = 0; _i < 2; ++_i) \
;         __builtin_amdgcn_global_load_lds((const unsigned*)((const char*)(gbase) + (size_t)_i * qstep + (voff)[0]), (PG8_LAS unsigned*)(lds + (bufoff) + ldsw + _i * 8192), 16, 0, 0); } while (0)
; #define PG8_LDA(dst, b, h) do { _Pragma("unroll") for (int m = 0; m < 4; ++m) _Pragma("unroll") for (int k = 0; k < 2; ++k) dst[m][k] = *(const PG8_LAS bf16x8*)(lds + PG8_SA(b, h) + aoff + m * 2048 + k * 1024); } while (0)
; #define PG8_LDB(dst, b, h) do { _Pragma("unroll") for (int n = 0; n < 2; ++n) _Pragma("unroll") for (int k = 0; k < 2; ++k) dst[n][k] = *(const PG8_LAS bf16x8*)(lds + PG8_SB(b, h) + boff + n * 2048 + k * 1024); } while (0)
; #define PG8_MMA(ai, bj, At, Bt) do { __builtin_amdgcn_s_setprio(1); _Pragma("unroll") for (int m = 0; m < 4; ++m) _Pragma("unroll") for (int n = 0; n < 2; ++n) _Pragma("unroll") for (int k = 0; k < 2; ++k) \
;         acc[ai][bj][m][n] = __builtin_amdgcn_mfma_f32_16x16x32_bf16(Bt[n][k], At[m][k], acc[ai][bj][m][n], 0, 0, 0); __builtin_amdgcn_s_setprio(0); } while (0)
; #define PG8_WAIT_V89() do { if constexpr (SLIVER) PG8_WAIT_V(9); else PG8_WAIT_V(8); } while (0)
; #define PG8_STAGE_S(b, gbase) do { if constexpr (SLIVER) __builtin_amdgcn_global_load_lds((const unsigned*)((const char*)(gbase) + voffS), (PG8_LAS unsigned*)(lds + STAGE_BYTES + (b) * 2048 + wid * 256), 4, 0, 0); } while (0)
; #define PG8_WAIT_L(n) asm volatile("s_waitcnt lgkmcnt(" #n ")" ::: "memory")
; #define PG8_BAR __builtin_amdgcn_s_barrier()
; #define PG8_SCHED __builtin_amdgcn_sched_barrier(0)
; template <class Epi, class Sched, bool ALIGN_EPI = false, bool SP2 = false, bool SLIVER = false>
; __device__ __forceinline__ void gemm_phase(PG8_LAS unsigned char* lds, const Gemm g, const Sched& S, const Epi& E) {
;     ...
;             PG8_LDB(B0, 1, 0); PG8_LDB(B1, 1, 1); PG8_SCHED; PG8_LDA(At, 1, 0); PG8_STAGE(PG8_SA(0, 1), a2 + hstep, voffA); PG8_STAGE_S(0, s2);
;             PG8_WAIT_V89(); PG8_WAIT_L(0); PG8_BAR; PG8_MMA(0, 0, At, B0); PG8_MMA(0, 1, At, B1); PG8_BAR; PG8_SCHED;
.LBB0_938:
	s_barrier
	s_setprio 0
	s_add_u32 s12, s54, s62
	s_addc_u32 s13, s55, s63
	s_add_u32 s68, s12, 0x100
	s_addc_u32 s69, s13, 0
	s_and_b64 s[12:13], s[80:81], exec
	s_cselect_b32 s13, s19, s69
	s_cselect_b32 s12, s18, s68
	s_add_i32 s68, 0, 0x18000
	v_add_u32_e32 v2, s68, v212
	s_add_i32 s69, 0, 0x1c000
	ds_read_b128 v[146:149], v2
	ds_read_b128 v[150:153], v2 offset:1024
	ds_read_b128 v[154:157], v2 offset:2048
	ds_read_b128 v[158:161], v2 offset:3072
	v_add_u32_e32 v2, s69, v212
	ds_read_b128 v[166:169], v2
	ds_read_b128 v[170:173], v2 offset:1024
	ds_read_b128 v[174:177], v2 offset:2048
	ds_read_b128 v[162:165], v2 offset:3072
	s_mov_b32 m0, s49
	v_lshl_add_u64 v[208:209], v[210:211], 0, s[46:47]
	ds_read_b128 v[2:5], v215 offset:32768
	ds_read_b128 v[6:9], v215 offset:33792
	ds_read_b128 v[180:183], v215 offset:34816
	ds_read_b128 v[184:187], v215 offset:35840
	ds_read_b128 v[216:219], v215 offset:36864
	ds_read_b128 v[220:223], v215 offset:37888
	ds_read_b128 v[224:227], v215 offset:38912
	ds_read_b128 v[228:231], v215 offset:39936
	global_load_lds_dwordx4 v[208:209], off
	v_lshl_add_u64 v[208:209], v[210:211], 0, s[6:7]
	s_mov_b32 m0, s88
	s_nop 0
	global_load_lds_dwordx4 v[208:209], off
	v_lshl_add_u64 v[208:209], s[12:13], 0, v[192:193]
	s_mov_b32 m0, s89
	s_nop 0
	global_load_lds_dword v[208:209], off
	s_waitcnt vmcnt(9)
	s_waitcnt lgkmcnt(0)
	s_setprio 1
	s_barrier
	v_mfma_f32_16x16x32_bf16 v[134:137], v[146:149], v[2:5], v[134:137]
	v_mfma_f32_16x16x32_bf16 v[130:133], v[154:157], v[2:5], v[130:133]
	v_mfma_f32_16x16x32_bf16 v[126:129], v[146:149], v[180:183], v[126:129]
	v_mfma_f32_16x16x32_bf16 v[122:125], v[154:157], v[180:183], v[122:125]
	v_mfma_f32_16x16x32_bf16 v[114:117], v[146:149], v[216:219], v[114:117]
	v_mfma_f32_16x16x32_bf16 v[106:109], v[154:157], v[216:219], v[106:109]
	v_mfma_f32_16x16x32_bf16 v[98:101], v[146:149], v[224:227], v[98:101]
	v_mfma_f32_16x16x32_bf16 v[90:93], v[154:157], v[224:227], v[90:93]
	v_mfma_f32_16x16x32_bf16 v[134:137], v[150:153], v[6:9], v[134:137]
	v_mfma_f32_16x16x32_bf16 v[130:133], v[158:161], v[6:9], v[130:133]
	v_mfma_f32_16x16x32_bf16 v[126:129], v[150:153], v[184:187], v[126:129]
	v_mfma_f32_16x16x32_bf16 v[122:125], v[158:161], v[184:187], v[122:125]
	v_mfma_f32_16x16x32_bf16 v[114:117], v[150:153], v[220:223], v[114:117]
	v_mfma_f32_16x16x32_bf16 v[106:109], v[158:161], v[220:223], v[106:109]
	v_mfma_f32_16x16x32_bf16 v[98:101], v[150:153], v[228:231], v[98:101]
	v_mfma_f32_16x16x32_bf16 v[90:93], v[158:161], v[228:231], v[90:93]
	s_setprio 0
	s_setprio 1
	v_mfma_f32_16x16x32_bf16 v[118:121], v[166:169], v[2:5], v[118:121]
	v_mfma_f32_16x16x32_bf16 v[2:5], v[174:177], v[2:5], v[110:113]
	v_mfma_f32_16x16x32_bf16 v[110:113], v[162:165], v[6:9], v[2:5]
	v_mfma_f32_16x16x32_bf16 v[2:5], v[166:169], v[180:183], v[102:105]
	v_mfma_f32_16x16x32_bf16 v[102:105], v[170:173], v[184:187], v[2:5]
	v_mfma_f32_16x16x32_bf16 v[2:5], v[174:177], v[180:183], v[94:97]
	v_mfma_f32_16x16x32_bf16 v[94:97], v[162:165], v[184:187], v[2:5]
	v_mfma_f32_16x16x32_bf16 v[2:5], v[166:169], v[216:219], v[86:89]
	v_mfma_f32_16x16x32_bf16 v[86:89], v[170:173], v[220:223], v[2:5]
	v_mfma_f32_16x16x32_bf16 v[2:5], v[174:177], v[216:219], v[82:85]
	v_mfma_f32_16x16x32_bf16 v[82:85], v[162:165], v[220:223], v[2:5]
	v_mfma_f32_16x16x32_bf16 v[2:5], v[166:169], v[224:227], v[78:81]
	v_mfma_f32_16x16x32_bf16 v[78:81], v[170:173], v[228:231], v[2:5]
	v_mfma_f32_16x16x32_bf16 v[2:5], v[174:177], v[224:227], v[74:77]
	v_mfma_f32_16x16x32_bf16 v[118:121], v[170:173], v[6:9], v[118:121]
	v_mfma_f32_16x16x32_bf16 v[74:77], v[162:165], v[228:231], v[2:5]
	s_barrier
; #define PG8_SB(B) __builtin_amdgcn_rcpf(1.f + expneg(B))
; #define PG8_SB(B) __builtin_amdgcn_rcpf(1.f + expneg(B))
; #define PG8_STAGE(bufoff, gbase, voff) do { _Pragma("unroll") for (int _i = 0; _i < 2; ++_i) \
;         __builtin_amdgcn_global_load_lds((const unsigned*)((const char*)(gbase) + (size_t)_i * qstep + (voff)[0]), (PG8_LAS unsigned*)(lds + (bufoff) + ldsw + _i * 8192), 16, 0, 0); } while (0)
; #define PG8_LDA(dst, b, h) do { _Pragma("unroll") for (int m = 0; m < 4; ++m) _Pragma("unroll") for (int k = 0; k < 2; ++k) dst[m][k] = *(const PG8_LAS bf16x8*)(lds + PG8_SA(b, h) + aoff + m * 2048 + k * 1024); } while (0)
; #define PG8_MMA(ai, bj, At, Bt) do { __builtin_amdgcn_s_setprio(1); _Pragma("unroll") for (int m = 0; m < 4; ++m) _Pragma("unroll") for (int n = 0; n < 2; ++n) _Pragma("unroll") for (int k = 0; k < 2; ++k) \
;         acc[ai][bj][m][n] = __builtin_amdgcn_mfma_f32_16x16x32_bf16(Bt[n][k], At[m][k], acc[ai][bj][m][n], 0, 0, 0); __builtin_amdgcn_s_setprio(0); } while (0)
; #define PG8_WAIT_V89() do { if constexpr (SLIVER) PG8_WAIT_V(9); else PG8_WAIT_V(8); } while (0)
; #define PG8_LDS_S(b) do { if constexpr (SLIVER) { Sf[0] = *(const PG8_LAS bf16x8*)(lds + STAGE_BYTES + (b) * 2048 + soff0); Sf[1] = *(const PG8_LAS bf16x8*)(lds + STAGE_BYTES + (b) * 2048 + (soff0 ^ 64)); } } while (0)
; #define PG8_WAIT_L(n) asm volatile("s_waitcnt lgkmcnt(" #n ")" ::: "memory")
; #define PG8_BAR __builtin_amdgcn_s_barrier()
; #define PG8_SCHED __builtin_amdgcn_sched_barrier(0)
; template <class Epi, class Sched, bool ALIGN_EPI = false, bool SP2 = false, bool SLIVER = false>
; __device__ __forceinline__ void gemm_phase(PG8_LAS unsigned char* lds, const Gemm g, const Sched& S, const Epi& E) {
;     ...
;             PG8_LDA(At, 1, 1); PG8_LDS_S(1); PG8_STAGE(PG8_SB(1, 0), b3, voffB); PG8_STAGE(PG8_SB(1, 1), b3 + hstep, voffB); PG8_STAGE(PG8_SA(1, 0), a3, voffA);
;             PG8_WAIT_V89(); PG8_WAIT_L(0); PG8_BAR; PG8_MMA(1, 0, At, B0); PG8_MMA(1, 1, At, B1); PG8_MMA_S(); PG8_BAR; PG8_SCHED;
	s_setprio 0
	s_add_i32 s12, 0, 0x20800
	v_add_u32_e32 v178, s12, v213
	v_add_u32_e32 v184, s12, v214
	s_add_i32 s12, s68, s92
	v_lshl_add_u64 v[208:209], v[202:203], 0, s[26:27]
	s_mov_b32 m0, s12
	ds_read_b128 v[2:5], v215 offset:49152
	ds_read_b128 v[6:9], v215 offset:50176
	ds_read_b128 v[216:219], v215 offset:51200
	ds_read_b128 v[220:223], v215 offset:52224
	ds_read_b128 v[224:227], v215 offset:53248
	ds_read_b128 v[228:231], v215 offset:54272
	ds_read_b128 v[232:235], v215 offset:55296
	ds_read_b128 v[240:243], v215 offset:56320
	ds_read_b128 v[180:183], v178
	ds_read_b128 v[184:187], v184
	global_load_lds_dwordx4 v[208:209], off
	v_lshl_add_u64 v[208:209], v[202:203], 0, s[58:59]
	s_add_i32 m0, s12, 0x2000
	s_mov_b64 s[12:13], 0x90080
	global_load_lds_dwordx4 v[208:209], off
	v_lshl_add_u64 v[208:209], v[202:203], 0, s[12:13]
	s_add_i32 s12, s69, s92
	s_mov_b32 m0, s12
	s_mov_b64 s[68:69], 0xd8080
	global_load_lds_dwordx4 v[208:209], off
	v_lshl_add_u64 v[202:203], v[202:203], 0, s[68:69]
	s_add_i32 m0, s12, 0x2000
	s_nop 0
	global_load_lds_dwordx4 v[202:203], off
	v_lshl_add_u64 v[202:203], v[210:211], 0, s[26:27]
	s_mov_b32 m0, s51
	s_nop 0
	global_load_lds_dwordx4 v[202:203], off
	v_lshl_add_u64 v[202:203], v[210:211], 0, s[58:59]
	s_mov_b32 m0, s53
	s_nop 0
	global_load_lds_dwordx4 v[202:203], off
	s_waitcnt vmcnt(9)
	s_waitcnt lgkmcnt(0)
	s_setprio 1
	s_barrier
	v_mfma_f32_16x16x32_bf16 v[70:73], v[146:149], v[2:5], v[70:73]
	v_mfma_f32_16x16x32_bf16 v[66:69], v[154:157], v[2:5], v[66:69]
	v_mfma_f32_16x16x32_bf16 v[62:65], v[146:149], v[216:219], v[62:65]
	v_mfma_f32_16x16x32_bf16 v[58:61], v[154:157], v[216:219], v[58:61]
	v_mfma_f32_16x16x32_bf16 v[50:53], v[146:149], v[224:227], v[50:53]
	v_mfma_f32_16x16x32_bf16 v[42:45], v[154:157], v[224:227], v[42:45]
	v_mfma_f32_16x16x32_bf16 v[34:37], v[146:149], v[232:235], v[34:37]
	v_mfma_f32_16x16x32_bf16 v[26:29], v[154:157], v[232:235], v[26:29]
	v_mfma_f32_16x16x32_bf16 v[70:73], v[150:153], v[6:9], v[70:73]
	v_mfma_f32_16x16x32_bf16 v[66:69], v[158:161], v[6:9], v[66:69]
	v_mfma_f32_16x16x32_bf16 v[62:65], v[150:153], v[220:223], v[62:65]
	v_mfma_f32_16x16x32_bf16 v[58:61], v[158:161], v[220:223], v[58:61]
	v_mfma_f32_16x16x32_bf16 v[50:53], v[150:153], v[228:231], v[50:53]
	v_mfma_f32_16x16x32_bf16 v[42:45], v[158:161], v[228:231], v[42:45]
	v_mfma_f32_16x16x32_bf16 v[34:37], v[150:153], v[240:243], v[34:37]
	v_mfma_f32_16x16x32_bf16 v[26:29], v[158:161], v[240:243], v[26:29]
	s_setprio 0
	s_setprio 1
	v_mfma_f32_16x16x32_bf16 v[54:57], v[166:169], v[2:5], v[54:57]
	v_mfma_f32_16x16x32_bf16 v[2:5], v[174:177], v[2:5], v[46:49]
	v_mfma_f32_16x16x32_bf16 v[46:49], v[162:165], v[6:9], v[2:5]
	v_mfma_f32_16x16x32_bf16 v[2:5], v[166:169], v[216:219], v[38:41]
	v_mfma_f32_16x16x32_bf16 v[38:41], v[170:173], v[220:223], v[2:5]
	v_mfma_f32_16x16x32_bf16 v[2:5], v[174:177], v[216:219], v[30:33]
	v_mfma_f32_16x16x32_bf16 v[30:33], v[162:165], v[220:223], v[2:5]
	v_mfma_f32_16x16x32_bf16 v[2:5], v[166:169], v[224:227], v[22:25]
	v_mfma_f32_16x16x32_bf16 v[22:25], v[170:173], v[228:231], v[2:5]
	v_mfma_f32_16x16x32_bf16 v[2:5], v[174:177], v[224:227], v[18:21]
	v_mfma_f32_16x16x32_bf16 v[18:21], v[162:165], v[228:231], v[2:5]
	v_mfma_f32_16x16x32_bf16 v[2:5], v[166:169], v[232:235], v[14:17]
	v_mfma_f32_16x16x32_bf16 v[14:17], v[170:173], v[240:243], v[2:5]
	v_mfma_f32_16x16x32_bf16 v[2:5], v[174:177], v[232:235], v[10:13]
	v_mfma_f32_16x16x32_bf16 v[54:57], v[170:173], v[6:9], v[54:57]
	v_mfma_f32_16x16x32_bf16 v[10:13], v[162:165], v[240:243], v[2:5]
	s_setprio 0
	s_setprio 1
	s_and_b64 vcc, exec, s[90:91]
	s_cbranch_vccz .Lslv_c3
	v_mfma_f32_16x16x32_bf16 v[2:5], v[166:169], v[180:183], v[138:141]
	v_mfma_f32_16x16x32_bf16 v[6:9], v[170:173], v[184:187], v[2:5]
	v_mfma_f32_16x16x32_bf16 v[2:5], v[174:177], v[180:183], v[142:145]
	v_mfma_f32_16x16x32_bf16 v[2:5], v[162:165], v[184:187], v[2:5]
	s_branch .LBB0_933
